# merge GEMM layer-1 third round: 4-way K-segment sharing of the 16 leftover units (owner keeps the gate rescale steps)
# baseline (speedup 1.0000x reference)
; #define LAS __attribute__((address_space(3)))
; #define PG8_STAGE(bufoff, gbase, voff) do { _Pragma("unroll") for (int _i = 0; _i < 2; ++_i) \
;         __builtin_amdgcn_global_load_lds((const unsigned*)((const char*)(gbase) + (voff)[_i]), (LAS unsigned*)(lds + (bufoff) + ldsw + _i * 8192), 16, 0, 0); } while (0)
; #define PG8_WAIT_V(n) asm volatile("s_waitcnt vmcnt(" #n ")" ::: "memory")
; #define PG8_BAR __builtin_amdgcn_s_barrier()
; template <class Epi, int LDA, int LDB, int KK>
; __device__ __forceinline__ void gemm_phase(int wv, LAS unsigned char* lds, const Gemm g, const StaticOrder& S, const Epi& E) {
;     ...
;     const char* cA = (const char*)g.A + (size_t)cur.pm * tstepA; const char* cB = (const char*)g.Bt + (size_t)cur.pn * tstepB;
;     if constexpr (Epi::ROWSCALE) { if (wid < 4) __builtin_amdgcn_global_load_lds((const unsigned*)(E.rsq + cur.pm * 256 + wid * 64 + lane), (LAS unsigned*)(lds + 131072 + wid * 256), 4, 0, 0); }
;     PG8_STAGE(PG8_SB(0, 0), cB, voffB); PG8_STAGE(PG8_SA(0, 0), cA, voffA); PG8_STAGE(PG8_SB(0, 1), cB + hstepB, voffB); PG8_STAGE(PG8_SA(0, 1), cA + hstepA, voffA);
;     if (wr == 1) PG8_BAR;
;     PG8_WAIT_V(4); PG8_BAR;
;     PG8_STAGE(PG8_SB(1, 0), cB + kstep, voffB); PG8_STAGE(PG8_SA(1, 0), cA + kstep, voffA); PG8_STAGE(PG8_SB(1, 1), cB + hstepB + kstep, voffB);
;     PG8_WAIT_V(6); PG8_BAR;
.LBB0_515:
	s_add_u32 s6, s10, 0x16b00000
	v_lshrrev_b32_e32 v11, 1, v2
	s_addc_u32 s7, s11, 0
	v_and_b32_e32 v11, 24, v11
	s_add_u32 s10, s10, 0x8400000
	v_and_b32_e32 v10, 15, v2
	v_lshlrev_b32_e32 v12, 1, v11
	v_lshlrev_b32_e32 v2, 2, v2
	s_sext_i32_i8 s23, s4
	s_addc_u32 s11, s11, 0
	v_lshl_or_b32 v197, s12, 6, v10
	v_lshl_or_b32 v10, v10, 6, v12
	s_lshl_b32 s4, s12, 13
	v_and_b32_e32 v2, 32, v2
	v_bitop3_b32 v12, v10, s4, v2 bitop3:0xde
	s_lshl_b32 s4, s5, 5
	s_and_b32 s12, s4, 0x60
	s_add_i32 m0, s36, 0x18000
	v_lshl_add_u64 v[8:9], v[8:9], 0, s[58:59]
	s_lshl_b32 s4, s12, 7
	s_waitcnt vmcnt(4)
	s_barrier
	global_load_lds_dwordx4 v[8:9], off
	v_lshl_add_u64 v[6:7], v[6:7], 0, s[58:59]
	s_add_i32 m0, s36, 0x1a000
	s_add_i32 s40, s36, 0x8000
	s_add_i32 s41, s36, 0xa000
	v_bitop3_b32 v216, v10, s4, v2 bitop3:0xde
	global_load_lds_dwordx4 v[6:7], off
	v_lshl_add_u64 v[4:5], v[4:5], 0, s[58:59]
	s_mov_b32 m0, s40
	s_add_u32 s4, s24, 0x80080
	global_load_lds_dwordx4 v[4:5], off
	v_lshl_add_u64 v[0:1], v[0:1], 0, s[58:59]
	s_mov_b32 m0, s41
	s_addc_u32 s5, s25, 0
	global_load_lds_dwordx4 v[0:1], off
	s_add_i32 m0, s36, 0x1c000
	v_lshl_add_u64 v[0:1], s[4:5], 0, v[206:207]
	global_load_lds_dwordx4 v[0:1], off
	v_lshl_add_u64 v[0:1], s[4:5], 0, v[202:203]
	s_add_i32 m0, s36, 0x1e000
	v_or_b32_e32 v217, s12, v11
	global_load_lds_dwordx4 v[0:1], off
	s_add_u32 s98, s20, 0x80080
	s_addc_u32 s99, s21, 0
	v_lshl_add_u64 v[230:231], s[98:99], 0, v[208:209]
	s_add_i32 m0, s36, 0xc000
	s_nop 0
	global_load_lds_dwordx4 v[230:231], off
	v_lshl_add_u64 v[230:231], s[98:99], 0, v[204:205]
	s_add_i32 m0, s36, 0xe000
	s_nop 0
	global_load_lds_dwordx4 v[230:231], off
	s_waitcnt vmcnt(8)
	s_mov_b32 s42, 0
	v_add_u32_e32 v218, 0, v12
	s_barrier
	s_mov_b32 s101, 0
	s_branch .LBB0_517

;     __device__ bool next(int i, Unit& u) const {
;         const long L = (long)i * G + c; if (L >= nwg) return false;
;         int wgid = (int)L; { const int q = nwg / NXCD, r = nwg % NXCD, xcd = wgid % NXCD, off = wgid / NXCD; wgid = (xcd < r ? xcd * (q + 1) : r * (q + 1) + (xcd - r) * q) + off; }
;         const int nig = WGM * nN, gid = wgid / nig, fm = gid * WGM, gsz = (nM - fm) < WGM ? (nM - fm) : WGM;
;         u.pm = fm + ((wgid % nig) % gsz); u.pn = (wgid % nig) / gsz; return true;
; template <class Epi, int LDA, int LDB, int KK>
; __device__ __forceinline__ void gemm_phase(int wv, LAS unsigned char* lds, const Gemm g, const StaticOrder& S, const Epi& E) {
;     ...
;         const bool has_next = S.next(ui + 1, nxt);
;         const char* nA = has_next ? (const char*)g.A + (size_t)nxt.pm * tstepA : cA; const char* nB = has_next ? (const char*)g.Bt + (size_t)nxt.pn * tstepB : cB;
;         if constexpr (Epi::ROWSCALE) { if (has_next && wid < 4) __builtin_amdgcn_global_load_lds((const unsigned*)(E.rsq + nxt.pm * 256 + wid * 64 + lane), (LAS unsigned*)(lds + 131072 + ((ui + 1) % 3) * 1024 + wid * 256), 4, 0, 0); }
;         for (int seg = 0, t = 0; seg < Epi::NSEG; ++seg) {
;           const int tend = Epi::HAS_MID ? (seg == 0 ? Epi::MID1 : (seg == 1 ? Epi::MID2 : nt)) : nt;
;           for (; t < tend; t += 2) {
;             const bool last = (t == nt - 2);
;             const char* a1 = cA + (size_t)(t + 1) * kstep;
;             const char* a2 = last ? nA : cA + (size_t)(t + 2) * kstep; const char* b2 = last ? nB : cB + (size_t)(t + 2) * kstep;
;             const char* a3 = a2 + kstep; const char* b3 = b2 + kstep;
;             PG8_LDB(B0, 0, 0); PG8_SCHED; PG8_LDA(At, 0, 0); PG8_STAGE(PG8_SA(1, 1), a1 + hstepA, voffA);
;             PG8_WAIT_L(8); PG8_BAR; PG8_WAIT_L(0); PG8_MMA(0, 0, At, B0); PG8_BAR; PG8_SCHED;
;             PG8_LDB(B1, 0, 1); PG8_STAGE(PG8_SB(0, 0), b2, voffB);
;             PG8_BAR; PG8_WAIT_L(0); PG8_MMA(0, 1, At, B1); PG8_BAR;
;             PG8_LDA(At, 0, 1); PG8_STAGE(PG8_SA(0, 0), a2, voffA);
;             PG8_BAR; PG8_WAIT_L(0); PG8_MMA(1, 0, At, B0); PG8_BAR; PG8_SCHED;
;             PG8_STAGE(PG8_SB(0, 1), b2 + hstepB, voffB);
;             PG8_WAIT_V(6); PG8_BAR; PG8_MMA(1, 1, At, B1); PG8_BAR;
;             PG8_LDB(B0, 1, 0); PG8_SCHED; PG8_LDA(At, 1, 0); PG8_STAGE(PG8_SA(0, 1), a2 + hstepA, voffA);
.LBB0_517:
	s_mov_b32 s100, s101
	s_add_i32 s42, s42, 1
	s_mul_i32 s4, s42, s49
	s_mul_hi_u32 s5, s42, s48
	s_add_i32 s5, s5, s4
	s_mul_i32 s4, s42, s48
	s_add_u32 s16, s4, s28
	s_addc_u32 s17, s5, s35
	s_mov_b32 s101, 0
	s_cmp_eq_u32 s2, 0
	s_cbranch_scc1 .Lmt_h1
	s_cmp_lt_u32 s16, 0x200
	s_cbranch_scc1 .Lmt_h1
	s_sub_u32 s98, s16, 0x200
	s_lshr_b32 s99, s98, 4
	s_and_b32 s98, s98, 15
	s_add_u32 s16, s98, 0x200
	s_add_u32 s101, s99, 1
	s_cmp_lt_u32 s99, 4
	s_cbranch_scc1 .Lmt_h1
	s_movk_i32 s16, 0x210
	s_mov_b32 s101, 0
.Lmt_h1:
	v_cmp_gt_i64_e64 s[4:5], s[16:17], v[198:199]
	s_and_b64 vcc, exec, s[4:5]
	s_cbranch_vccnz .LBB0_519
	s_ashr_i32 s12, s16, 31
	s_lshr_b32 s12, s12, 29
	s_add_i32 s12, s16, s12
	s_ashr_i32 s13, s12, 3
	s_and_b32 s12, s12, -8
	s_sub_i32 s12, s16, s12
	s_cmp_lt_i32 s12, 0
	s_movk_i32 s14, 0x43
	s_cselect_b32 s14, s14, 0x42
	s_mul_i32 s12, s14, s12
	s_add_i32 s12, s12, s13
	s_ashr_i32 s13, s12, 31
	s_lshr_b32 s13, s13, 26
	s_add_i32 s13, s12, s13
	s_ashr_i32 s14, s13, 6
	s_lshl_b32 s14, s14, 3
	s_sub_i32 s15, 0x42, s14
	s_min_i32 s15, s15, 8
	s_abs_i32 s18, s15
	v_cvt_f32_u32_e32 v0, s18
	s_sub_i32 s26, 0, s18
	s_andn2_b32 s13, s13, 63
	s_sub_i32 s13, s12, s13
	v_rcp_iflag_f32_e32 v0, v0
	s_abs_i32 s12, s13
	s_xor_b32 s19, s13, s15
	s_ashr_i32 s19, s19, 31
	v_mul_f32_e32 v0, 0x4f7ffffe, v0
	v_cvt_u32_f32_e32 v0, v0
	s_nop 0
	v_readfirstlane_b32 s27, v0
	s_mul_i32 s26, s26, s27
	s_mul_hi_u32 s26, s27, s26
	s_add_i32 s27, s27, s26
	s_mul_hi_u32 s26, s12, s27
	s_mul_i32 s27, s26, s18
	s_sub_i32 s12, s12, s27
	s_add_i32 s43, s26, 1
	s_sub_i32 s27, s12, s18
	s_cmp_ge_u32 s12, s18
	s_cselect_b32 s26, s43, s26
	s_cselect_b32 s12, s27, s12
	s_add_i32 s27, s26, 1
	s_cmp_ge_u32 s12, s18
	s_cselect_b32 s12, s27, s26
	s_xor_b32 s12, s12, s19
	s_sub_i32 s12, s12, s19
	s_mul_i32 s15, s12, s15
	s_sub_i32 s13, s13, s15
	s_add_i32 s14, s13, s14
.LBB0_519:
	s_ashr_i32 s15, s14, 31
	v_cmp_lt_i64_e32 vcc, s[16:17], v[200:201]
	s_lshl_b64 s[16:17], s[14:15], 20
	s_add_u32 s16, s8, s16
	s_addc_u32 s17, s9, s17
	s_sub_u32 s98, s101, 1
	s_max_i32 s98, s98, 0
	s_lshl_b32 s98, s98, 10
	s_add_u32 s16, s16, s98
	s_addc_u32 s17, s17, 0
	s_and_b64 s[18:19], vcc, exec
	s_cselect_b32 s15, s17, s21
	s_cselect_b32 s43, s16, s20
	s_ashr_i32 s13, s12, 31
	s_lshl_b64 s[18:19], s[12:13], 20
	s_add_u32 s18, s30, s18
	s_addc_u32 s19, s31, s19
	s_sub_u32 s98, s101, 1
	s_max_i32 s98, s98, 0
	s_lshl_b32 s98, s98, 10
	s_add_u32 s18, s18, s98
	s_addc_u32 s19, s19, 0
	s_and_b64 s[26:27], vcc, exec
	s_cselect_b32 s13, s19, s25
	s_cselect_b32 s44, s18, s24
	s_add_u32 s45, s24, 0x100
	v_lshl_or_b32 v212, s23, 8, v217
	s_addc_u32 s70, s25, 0
	v_mov_b32_e32 v2, v3
	v_ashrrev_i32_e32 v213, 31, v212
	s_add_u32 s71, s20, 0x100
	v_mov_b32_e32 v0, v3
	v_mov_b32_e32 v1, v3
	v_mov_b64_e32 v[6:7], v[2:3]
	v_mov_b64_e32 v[10:11], v[2:3]
	v_mov_b64_e32 v[22:23], v[2:3]
	v_mov_b64_e32 v[26:27], v[2:3]
	v_mov_b64_e32 v[38:39], v[2:3]
	v_mov_b64_e32 v[42:43], v[2:3]
	v_mov_b64_e32 v[54:55], v[2:3]
	v_mov_b64_e32 v[58:59], v[2:3]
	v_mov_b64_e32 v[14:15], v[2:3]
	v_mov_b64_e32 v[18:19], v[2:3]
	v_mov_b64_e32 v[30:31], v[2:3]
	v_mov_b64_e32 v[34:35], v[2:3]
	v_mov_b64_e32 v[46:47], v[2:3]
	v_mov_b64_e32 v[50:51], v[2:3]
	v_mov_b64_e32 v[62:63], v[2:3]
	v_mov_b64_e32 v[66:67], v[2:3]
	v_mov_b64_e32 v[70:71], v[2:3]
	v_mov_b64_e32 v[74:75], v[2:3]
	v_mov_b64_e32 v[86:87], v[2:3]
	v_mov_b64_e32 v[90:91], v[2:3]
	v_mov_b64_e32 v[102:103], v[2:3]
	v_mov_b64_e32 v[106:107], v[2:3]
	v_mov_b64_e32 v[118:119], v[2:3]
	v_mov_b64_e32 v[122:123], v[2:3]
	v_mov_b64_e32 v[78:79], v[2:3]
	v_mov_b64_e32 v[82:83], v[2:3]
	v_mov_b64_e32 v[94:95], v[2:3]
	v_mov_b64_e32 v[98:99], v[2:3]
	v_mov_b64_e32 v[110:111], v[2:3]
	v_mov_b64_e32 v[114:115], v[2:3]
	v_mov_b64_e32 v[126:127], v[2:3]
	v_mov_b64_e32 v[130:131], v[2:3]
	v_lshl_add_u32 v210, s22, 8, v197
	v_lshl_add_u64 v[214:215], v[212:213], 1, s[6:7]
	s_addc_u32 s73, s21, 0
	s_mov_b32 s22, 0
	v_mov_b64_e32 v[4:5], v[0:1]
	v_mov_b64_e32 v[8:9], v[0:1]
	v_mov_b64_e32 v[20:21], v[0:1]
	v_mov_b64_e32 v[24:25], v[0:1]
	v_mov_b64_e32 v[36:37], v[0:1]
	v_mov_b64_e32 v[40:41], v[0:1]
	v_mov_b64_e32 v[52:53], v[0:1]
	v_mov_b64_e32 v[56:57], v[0:1]
	v_mov_b64_e32 v[12:13], v[0:1]
	v_mov_b64_e32 v[16:17], v[0:1]
	v_mov_b64_e32 v[28:29], v[0:1]
	v_mov_b64_e32 v[32:33], v[0:1]
	v_mov_b64_e32 v[44:45], v[0:1]
	v_mov_b64_e32 v[48:49], v[0:1]
	v_mov_b64_e32 v[60:61], v[0:1]
	v_mov_b64_e32 v[64:65], v[0:1]
	v_mov_b64_e32 v[68:69], v[0:1]
	v_mov_b64_e32 v[72:73], v[0:1]
	v_mov_b64_e32 v[84:85], v[0:1]
	v_mov_b64_e32 v[88:89], v[0:1]
	v_mov_b64_e32 v[100:101], v[0:1]
	v_mov_b64_e32 v[104:105], v[0:1]
	v_mov_b64_e32 v[116:117], v[0:1]
	v_mov_b64_e32 v[120:121], v[0:1]
	v_mov_b64_e32 v[76:77], v[0:1]
	v_mov_b64_e32 v[80:81], v[0:1]
	v_mov_b64_e32 v[92:93], v[0:1]
	v_mov_b64_e32 v[96:97], v[0:1]
	v_mov_b64_e32 v[108:109], v[0:1]
	v_mov_b64_e32 v[112:113], v[0:1]
	v_mov_b64_e32 v[124:125], v[0:1]
	v_mov_b64_e32 v[128:129], v[0:1]
	s_mov_b32 s74, 0
	s_branch .LBB0_521

; template <class Epi, int LDA, int LDB, int KK>
; __device__ __forceinline__ void gemm_phase(int wv, LAS unsigned char* lds, const Gemm g, const StaticOrder& S, const Epi& E) {
;     ...
;         for (int seg = 0, t = 0; seg < Epi::NSEG; ++seg) {
;           const int tend = Epi::HAS_MID ? (seg == 0 ? Epi::MID1 : (seg == 1 ? Epi::MID2 : nt)) : nt;
;           for (; t < tend; t += 2) {
.LBB0_521:
	s_cmp_eq_u32 s74, 1
	s_cselect_b32 s23, 24, 32
	s_cmp_lg_u32 s74, 0
	s_cselect_b32 s46, s23, 8
	s_cmp_eq_u32 s100, 1
	s_cbranch_scc0 .Lmt_no
	s_cmp_eq_u32 s74, 0
	s_cbranch_scc1 .Lmt_no
	s_cmp_ge_i32 s22, s46
	s_cbranch_scc1 .Lmt_no
	s_cmp_eq_u32 s74, 2
	s_cbranch_scc1 .Lmt_s2
	s_cmp_lg_u32 s95, 0
	s_cbranch_scc1 .Lmt_o_wait
	s_and_b32 s98, s81, 15
	s_lshl_b32 s98, s98, 2
	s_add_u32 s98, s98, 0x201daa80
	s_add_u32 s98, s10, s98
	s_addc_u32 s99, s11, 0
	s_mov_b64 exec, 1
	v_mov_b32_e32 v132, 0
.Lmt_poll:
	s_sleep 2
	global_load_dword v133, v132, s[98:99] sc1
	s_waitcnt vmcnt(0)
	v_cmp_gt_u32_e32 vcc, 3, v133
	s_cbranch_vccnz .Lmt_poll
	buffer_inv sc1
	s_waitcnt vmcnt(0)
	s_mov_b64 exec, -1
.Lmt_o_wait:
	s_barrier
	s_and_b32 s98, s81, 15
	s_mul_i32 s98, s98, 3
	s_lshl_b32 s98, s98, 18
	s_add_u32 s98, s98, 0x7c00000
	s_add_u32 s98, s10, s98
	s_addc_u32 s99, s11, 0
	v_mbcnt_lo_u32_b32 v132, -1, 0
	v_mbcnt_hi_u32_b32 v132, -1, v132
	v_lshl_or_b32 v132, s95, 6, v132
	v_lshlrev_b32_e32 v132, 4, v132
	global_load_dwordx4 v[136:139], v132, s[98:99] sc0 sc1
	v_add_u32_e32 v132, 0x2000, v132
	global_load_dwordx4 v[140:143], v132, s[98:99] sc0 sc1
	v_add_u32_e32 v132, 0x2000, v132
	global_load_dwordx4 v[144:147], v132, s[98:99] sc0 sc1
	v_add_u32_e32 v132, 0x2000, v132
	global_load_dwordx4 v[148:151], v132, s[98:99] sc0 sc1
	v_add_u32_e32 v132, 0x2000, v132
	global_load_dwordx4 v[152:155], v132, s[98:99] sc0 sc1
	v_add_u32_e32 v132, 0x2000, v132
	global_load_dwordx4 v[156:159], v132, s[98:99] sc0 sc1
	v_add_u32_e32 v132, 0x2000, v132
	global_load_dwordx4 v[160:163], v132, s[98:99] sc0 sc1
	v_add_u32_e32 v132, 0x2000, v132
	global_load_dwordx4 v[164:167], v132, s[98:99] sc0 sc1
	v_add_u32_e32 v132, 0x2000, v132
	s_waitcnt vmcnt(7)
	v_pk_add_f32 v[4:5], v[4:5], v[136:137]
	v_pk_add_f32 v[6:7], v[6:7], v[138:139]
	s_waitcnt vmcnt(6)
	v_pk_add_f32 v[8:9], v[8:9], v[140:141]
	v_pk_add_f32 v[10:11], v[10:11], v[142:143]
	s_waitcnt vmcnt(5)
	v_pk_add_f32 v[12:13], v[12:13], v[144:145]
	v_pk_add_f32 v[14:15], v[14:15], v[146:147]
	s_waitcnt vmcnt(4)
	v_pk_add_f32 v[16:17], v[16:17], v[148:149]
	v_pk_add_f32 v[18:19], v[18:19], v[150:151]
	s_waitcnt vmcnt(3)
	v_pk_add_f32 v[20:21], v[20:21], v[152:153]
	v_pk_add_f32 v[22:23], v[22:23], v[154:155]
	s_waitcnt vmcnt(2)
	v_pk_add_f32 v[24:25], v[24:25], v[156:157]
	v_pk_add_f32 v[26:27], v[26:27], v[158:159]
	s_waitcnt vmcnt(1)
	v_pk_add_f32 v[28:29], v[28:29], v[160:161]
	v_pk_add_f32 v[30:31], v[30:31], v[162:163]
	s_waitcnt vmcnt(0)
	v_pk_add_f32 v[32:33], v[32:33], v[164:165]
	v_pk_add_f32 v[34:35], v[34:35], v[166:167]
	global_load_dwordx4 v[136:139], v132, s[98:99] sc0 sc1
	v_add_u32_e32 v132, 0x2000, v132
	global_load_dwordx4 v[140:143], v132, s[98:99] sc0 sc1
	v_add_u32_e32 v132, 0x2000, v132
	global_load_dwordx4 v[144:147], v132, s[98:99] sc0 sc1
	v_add_u32_e32 v132, 0x2000, v132
	global_load_dwordx4 v[148:151], v132, s[98:99] sc0 sc1
	v_add_u32_e32 v132, 0x2000, v132
	global_load_dwordx4 v[152:155], v132, s[98:99] sc0 sc1
	v_add_u32_e32 v132, 0x2000, v132
	global_load_dwordx4 v[156:159], v132, s[98:99] sc0 sc1
	v_add_u32_e32 v132, 0x2000, v132
	global_load_dwordx4 v[160:163], v132, s[98:99] sc0 sc1
	v_add_u32_e32 v132, 0x2000, v132
	global_load_dwordx4 v[164:167], v132, s[98:99] sc0 sc1
	v_add_u32_e32 v132, 0x2000, v132
	s_waitcnt vmcnt(7)
	v_pk_add_f32 v[36:37], v[36:37], v[136:137]
	v_pk_add_f32 v[38:39], v[38:39], v[138:139]
	s_waitcnt vmcnt(6)
	v_pk_add_f32 v[40:41], v[40:41], v[140:141]
	v_pk_add_f32 v[42:43], v[42:43], v[142:143]
	s_waitcnt vmcnt(5)
	v_pk_add_f32 v[44:45], v[44:45], v[144:145]
	v_pk_add_f32 v[46:47], v[46:47], v[146:147]
	s_waitcnt vmcnt(4)
	v_pk_add_f32 v[48:49], v[48:49], v[148:149]
	v_pk_add_f32 v[50:51], v[50:51], v[150:151]
	s_waitcnt vmcnt(3)
	v_pk_add_f32 v[52:53], v[52:53], v[152:153]
	v_pk_add_f32 v[54:55], v[54:55], v[154:155]
	s_waitcnt vmcnt(2)
	v_pk_add_f32 v[56:57], v[56:57], v[156:157]
	v_pk_add_f32 v[58:59], v[58:59], v[158:159]
	s_waitcnt vmcnt(1)
	v_pk_add_f32 v[60:61], v[60:61], v[160:161]
	v_pk_add_f32 v[62:63], v[62:63], v[162:163]
	s_waitcnt vmcnt(0)
	v_pk_add_f32 v[64:65], v[64:65], v[164:165]
	v_pk_add_f32 v[66:67], v[66:67], v[166:167]
	global_load_dwordx4 v[136:139], v132, s[98:99] sc0 sc1
	v_add_u32_e32 v132, 0x2000, v132
	global_load_dwordx4 v[140:143], v132, s[98:99] sc0 sc1
	v_add_u32_e32 v132, 0x2000, v132
	global_load_dwordx4 v[144:147], v132, s[98:99] sc0 sc1
	v_add_u32_e32 v132, 0x2000, v132
	global_load_dwordx4 v[148:151], v132, s[98:99] sc0 sc1
	v_add_u32_e32 v132, 0x2000, v132
	global_load_dwordx4 v[152:155], v132, s[98:99] sc0 sc1
	v_add_u32_e32 v132, 0x2000, v132
	global_load_dwordx4 v[156:159], v132, s[98:99] sc0 sc1
	v_add_u32_e32 v132, 0x2000, v132
	global_load_dwordx4 v[160:163], v132, s[98:99] sc0 sc1
	v_add_u32_e32 v132, 0x2000, v132
	global_load_dwordx4 v[164:167], v132, s[98:99] sc0 sc1
	v_add_u32_e32 v132, 0x2000, v132
	s_waitcnt vmcnt(7)
	v_pk_add_f32 v[68:69], v[68:69], v[136:137]
	v_pk_add_f32 v[70:71], v[70:71], v[138:139]
	s_waitcnt vmcnt(6)
	v_pk_add_f32 v[72:73], v[72:73], v[140:141]
	v_pk_add_f32 v[74:75], v[74:75], v[142:143]
	s_waitcnt vmcnt(5)
	v_pk_add_f32 v[76:77], v[76:77], v[144:145]
	v_pk_add_f32 v[78:79], v[78:79], v[146:147]
	s_waitcnt vmcnt(4)
	v_pk_add_f32 v[80:81], v[80:81], v[148:149]
	v_pk_add_f32 v[82:83], v[82:83], v[150:151]
	s_waitcnt vmcnt(3)
	v_pk_add_f32 v[84:85], v[84:85], v[152:153]
	v_pk_add_f32 v[86:87], v[86:87], v[154:155]
	s_waitcnt vmcnt(2)
	v_pk_add_f32 v[88:89], v[88:89], v[156:157]
	v_pk_add_f32 v[90:91], v[90:91], v[158:159]
	s_waitcnt vmcnt(1)
; template <class Epi, int LDA, int LDB, int KK>
; __device__ __forceinline__ void gemm_phase(int wv, LAS unsigned char* lds, const Gemm g, const StaticOrder& S, const Epi& E) {
;     ...
;         for (int seg = 0, t = 0; seg < Epi::NSEG; ++seg) {
;           const int tend = Epi::HAS_MID ? (seg == 0 ? Epi::MID1 : (seg == 1 ? Epi::MID2 : nt)) : nt;
;           for (; t < tend; t += 2) {
	v_pk_add_f32 v[92:93], v[92:93], v[160:161]
	v_pk_add_f32 v[94:95], v[94:95], v[162:163]
	s_waitcnt vmcnt(0)
	v_pk_add_f32 v[96:97], v[96:97], v[164:165]
	v_pk_add_f32 v[98:99], v[98:99], v[166:167]
	global_load_dwordx4 v[136:139], v132, s[98:99] sc0 sc1
	v_add_u32_e32 v132, 0x2000, v132
	global_load_dwordx4 v[140:143], v132, s[98:99] sc0 sc1
	v_add_u32_e32 v132, 0x2000, v132
	global_load_dwordx4 v[144:147], v132, s[98:99] sc0 sc1
	v_add_u32_e32 v132, 0x2000, v132
	global_load_dwordx4 v[148:151], v132, s[98:99] sc0 sc1
	v_add_u32_e32 v132, 0x2000, v132
	global_load_dwordx4 v[152:155], v132, s[98:99] sc0 sc1
	v_add_u32_e32 v132, 0x2000, v132
	global_load_dwordx4 v[156:159], v132, s[98:99] sc0 sc1
	v_add_u32_e32 v132, 0x2000, v132
	global_load_dwordx4 v[160:163], v132, s[98:99] sc0 sc1
	v_add_u32_e32 v132, 0x2000, v132
	global_load_dwordx4 v[164:167], v132, s[98:99] sc0 sc1
	v_add_u32_e32 v132, 0x2000, v132
	s_waitcnt vmcnt(7)
	v_pk_add_f32 v[100:101], v[100:101], v[136:137]
	v_pk_add_f32 v[102:103], v[102:103], v[138:139]
	s_waitcnt vmcnt(6)
	v_pk_add_f32 v[104:105], v[104:105], v[140:141]
	v_pk_add_f32 v[106:107], v[106:107], v[142:143]
	s_waitcnt vmcnt(5)
	v_pk_add_f32 v[108:109], v[108:109], v[144:145]
	v_pk_add_f32 v[110:111], v[110:111], v[146:147]
	s_waitcnt vmcnt(4)
	v_pk_add_f32 v[112:113], v[112:113], v[148:149]
	v_pk_add_f32 v[114:115], v[114:115], v[150:151]
	s_waitcnt vmcnt(3)
	v_pk_add_f32 v[116:117], v[116:117], v[152:153]
	v_pk_add_f32 v[118:119], v[118:119], v[154:155]
	s_waitcnt vmcnt(2)
	v_pk_add_f32 v[120:121], v[120:121], v[156:157]
	v_pk_add_f32 v[122:123], v[122:123], v[158:159]
	s_waitcnt vmcnt(1)
	v_pk_add_f32 v[124:125], v[124:125], v[160:161]
	v_pk_add_f32 v[126:127], v[126:127], v[162:163]
	s_waitcnt vmcnt(0)
	v_pk_add_f32 v[128:129], v[128:129], v[164:165]
	v_pk_add_f32 v[130:131], v[130:131], v[166:167]
	global_load_dwordx4 v[136:139], v132, s[98:99] sc0 sc1
	v_add_u32_e32 v132, 0x2000, v132
	global_load_dwordx4 v[140:143], v132, s[98:99] sc0 sc1
	v_add_u32_e32 v132, 0x2000, v132
	global_load_dwordx4 v[144:147], v132, s[98:99] sc0 sc1
	v_add_u32_e32 v132, 0x2000, v132
	global_load_dwordx4 v[148:151], v132, s[98:99] sc0 sc1
	v_add_u32_e32 v132, 0x2000, v132
	global_load_dwordx4 v[152:155], v132, s[98:99] sc0 sc1
	v_add_u32_e32 v132, 0x2000, v132
	global_load_dwordx4 v[156:159], v132, s[98:99] sc0 sc1
	v_add_u32_e32 v132, 0x2000, v132
	global_load_dwordx4 v[160:163], v132, s[98:99] sc0 sc1
	v_add_u32_e32 v132, 0x2000, v132
	global_load_dwordx4 v[164:167], v132, s[98:99] sc0 sc1
	v_add_u32_e32 v132, 0x2000, v132
	s_waitcnt vmcnt(7)
	v_pk_add_f32 v[4:5], v[4:5], v[136:137]
	v_pk_add_f32 v[6:7], v[6:7], v[138:139]
	s_waitcnt vmcnt(6)
	v_pk_add_f32 v[8:9], v[8:9], v[140:141]
	v_pk_add_f32 v[10:11], v[10:11], v[142:143]
	s_waitcnt vmcnt(5)
	v_pk_add_f32 v[12:13], v[12:13], v[144:145]
	v_pk_add_f32 v[14:15], v[14:15], v[146:147]
	s_waitcnt vmcnt(4)
	v_pk_add_f32 v[16:17], v[16:17], v[148:149]
	v_pk_add_f32 v[18:19], v[18:19], v[150:151]
	s_waitcnt vmcnt(3)
	v_pk_add_f32 v[20:21], v[20:21], v[152:153]
	v_pk_add_f32 v[22:23], v[22:23], v[154:155]
	s_waitcnt vmcnt(2)
	v_pk_add_f32 v[24:25], v[24:25], v[156:157]
	v_pk_add_f32 v[26:27], v[26:27], v[158:159]
	s_waitcnt vmcnt(1)
	v_pk_add_f32 v[28:29], v[28:29], v[160:161]
	v_pk_add_f32 v[30:31], v[30:31], v[162:163]
	s_waitcnt vmcnt(0)
	v_pk_add_f32 v[32:33], v[32:33], v[164:165]
	v_pk_add_f32 v[34:35], v[34:35], v[166:167]
	global_load_dwordx4 v[136:139], v132, s[98:99] sc0 sc1
	v_add_u32_e32 v132, 0x2000, v132
	global_load_dwordx4 v[140:143], v132, s[98:99] sc0 sc1
	v_add_u32_e32 v132, 0x2000, v132
	global_load_dwordx4 v[144:147], v132, s[98:99] sc0 sc1
	v_add_u32_e32 v132, 0x2000, v132
	global_load_dwordx4 v[148:151], v132, s[98:99] sc0 sc1
	v_add_u32_e32 v132, 0x2000, v132
	global_load_dwordx4 v[152:155], v132, s[98:99] sc0 sc1
	v_add_u32_e32 v132, 0x2000, v132
	global_load_dwordx4 v[156:159], v132, s[98:99] sc0 sc1
	v_add_u32_e32 v132, 0x2000, v132
	global_load_dwordx4 v[160:163], v132, s[98:99] sc0 sc1
	v_add_u32_e32 v132, 0x2000, v132
	global_load_dwordx4 v[164:167], v132, s[98:99] sc0 sc1
	v_add_u32_e32 v132, 0x2000, v132
	s_waitcnt vmcnt(7)
	v_pk_add_f32 v[36:37], v[36:37], v[136:137]
	v_pk_add_f32 v[38:39], v[38:39], v[138:139]
	s_waitcnt vmcnt(6)
	v_pk_add_f32 v[40:41], v[40:41], v[140:141]
	v_pk_add_f32 v[42:43], v[42:43], v[142:143]
	s_waitcnt vmcnt(5)
	v_pk_add_f32 v[44:45], v[44:45], v[144:145]
	v_pk_add_f32 v[46:47], v[46:47], v[146:147]
	s_waitcnt vmcnt(4)
	v_pk_add_f32 v[48:49], v[48:49], v[148:149]
	v_pk_add_f32 v[50:51], v[50:51], v[150:151]
	s_waitcnt vmcnt(3)
	v_pk_add_f32 v[52:53], v[52:53], v[152:153]
	v_pk_add_f32 v[54:55], v[54:55], v[154:155]
	s_waitcnt vmcnt(2)
	v_pk_add_f32 v[56:57], v[56:57], v[156:157]
	v_pk_add_f32 v[58:59], v[58:59], v[158:159]
	s_waitcnt vmcnt(1)
	v_pk_add_f32 v[60:61], v[60:61], v[160:161]
	v_pk_add_f32 v[62:63], v[62:63], v[162:163]
	s_waitcnt vmcnt(0)
	v_pk_add_f32 v[64:65], v[64:65], v[164:165]
	v_pk_add_f32 v[66:67], v[66:67], v[166:167]
	global_load_dwordx4 v[136:139], v132, s[98:99] sc0 sc1
	v_add_u32_e32 v132, 0x2000, v132
	global_load_dwordx4 v[140:143], v132, s[98:99] sc0 sc1
	v_add_u32_e32 v132, 0x2000, v132
	global_load_dwordx4 v[144:147], v132, s[98:99] sc0 sc1
	v_add_u32_e32 v132, 0x2000, v132
	global_load_dwordx4 v[148:151], v132, s[98:99] sc0 sc1
	v_add_u32_e32 v132, 0x2000, v132
	global_load_dwordx4 v[152:155], v132, s[98:99] sc0 sc1
	v_add_u32_e32 v132, 0x2000, v132
	global_load_dwordx4 v[156:159], v132, s[98:99] sc0 sc1
	v_add_u32_e32 v132, 0x2000, v132
	global_load_dwordx4 v[160:163], v132, s[98:99] sc0 sc1
	v_add_u32_e32 v132, 0x2000, v132
	global_load_dwordx4 v[164:167], v132, s[98:99] sc0 sc1
	v_add_u32_e32 v132, 0x2000, v132
	s_waitcnt vmcnt(7)
; template <class Epi, int LDA, int LDB, int KK>
; __device__ __forceinline__ void gemm_phase(int wv, LAS unsigned char* lds, const Gemm g, const StaticOrder& S, const Epi& E) {
;     ...
;         for (int seg = 0, t = 0; seg < Epi::NSEG; ++seg) {
;           const int tend = Epi::HAS_MID ? (seg == 0 ? Epi::MID1 : (seg == 1 ? Epi::MID2 : nt)) : nt;
;           for (; t < tend; t += 2) {
	v_pk_add_f32 v[68:69], v[68:69], v[136:137]
	v_pk_add_f32 v[70:71], v[70:71], v[138:139]
	s_waitcnt vmcnt(6)
	v_pk_add_f32 v[72:73], v[72:73], v[140:141]
	v_pk_add_f32 v[74:75], v[74:75], v[142:143]
	s_waitcnt vmcnt(5)
	v_pk_add_f32 v[76:77], v[76:77], v[144:145]
	v_pk_add_f32 v[78:79], v[78:79], v[146:147]
	s_waitcnt vmcnt(4)
	v_pk_add_f32 v[80:81], v[80:81], v[148:149]
	v_pk_add_f32 v[82:83], v[82:83], v[150:151]
	s_waitcnt vmcnt(3)
	v_pk_add_f32 v[84:85], v[84:85], v[152:153]
	v_pk_add_f32 v[86:87], v[86:87], v[154:155]
	s_waitcnt vmcnt(2)
	v_pk_add_f32 v[88:89], v[88:89], v[156:157]
	v_pk_add_f32 v[90:91], v[90:91], v[158:159]
	s_waitcnt vmcnt(1)
	v_pk_add_f32 v[92:93], v[92:93], v[160:161]
	v_pk_add_f32 v[94:95], v[94:95], v[162:163]
	s_waitcnt vmcnt(0)
	v_pk_add_f32 v[96:97], v[96:97], v[164:165]
	v_pk_add_f32 v[98:99], v[98:99], v[166:167]
	global_load_dwordx4 v[136:139], v132, s[98:99] sc0 sc1
	v_add_u32_e32 v132, 0x2000, v132
	global_load_dwordx4 v[140:143], v132, s[98:99] sc0 sc1
	v_add_u32_e32 v132, 0x2000, v132
	global_load_dwordx4 v[144:147], v132, s[98:99] sc0 sc1
	v_add_u32_e32 v132, 0x2000, v132
	global_load_dwordx4 v[148:151], v132, s[98:99] sc0 sc1
	v_add_u32_e32 v132, 0x2000, v132
	global_load_dwordx4 v[152:155], v132, s[98:99] sc0 sc1
	v_add_u32_e32 v132, 0x2000, v132
	global_load_dwordx4 v[156:159], v132, s[98:99] sc0 sc1
	v_add_u32_e32 v132, 0x2000, v132
	global_load_dwordx4 v[160:163], v132, s[98:99] sc0 sc1
	v_add_u32_e32 v132, 0x2000, v132
	global_load_dwordx4 v[164:167], v132, s[98:99] sc0 sc1
	s_waitcnt vmcnt(7)
	v_pk_add_f32 v[100:101], v[100:101], v[136:137]
	v_pk_add_f32 v[102:103], v[102:103], v[138:139]
	s_waitcnt vmcnt(6)
	v_pk_add_f32 v[104:105], v[104:105], v[140:141]
	v_pk_add_f32 v[106:107], v[106:107], v[142:143]
	s_waitcnt vmcnt(5)
	v_pk_add_f32 v[108:109], v[108:109], v[144:145]
	v_pk_add_f32 v[110:111], v[110:111], v[146:147]
	s_waitcnt vmcnt(4)
	v_pk_add_f32 v[112:113], v[112:113], v[148:149]
	v_pk_add_f32 v[114:115], v[114:115], v[150:151]
	s_waitcnt vmcnt(3)
	v_pk_add_f32 v[116:117], v[116:117], v[152:153]
	v_pk_add_f32 v[118:119], v[118:119], v[154:155]
	s_waitcnt vmcnt(2)
	v_pk_add_f32 v[120:121], v[120:121], v[156:157]
	v_pk_add_f32 v[122:123], v[122:123], v[158:159]
	s_waitcnt vmcnt(1)
	v_pk_add_f32 v[124:125], v[124:125], v[160:161]
	v_pk_add_f32 v[126:127], v[126:127], v[162:163]
	s_waitcnt vmcnt(0)
	v_pk_add_f32 v[128:129], v[128:129], v[164:165]
	v_pk_add_f32 v[130:131], v[130:131], v[166:167]
	s_branch .Lmt_sd
.Lmt_s2:
	s_and_b32 s98, s81, 15
	s_mul_i32 s98, s98, 3
	s_add_u32 s98, s98, 2
	s_lshl_b32 s98, s98, 18
	s_add_u32 s98, s98, 0x7c00000
	s_add_u32 s98, s10, s98
	s_addc_u32 s99, s11, 0
	v_mbcnt_lo_u32_b32 v132, -1, 0
	v_mbcnt_hi_u32_b32 v132, -1, v132
	v_lshl_or_b32 v132, s95, 6, v132
	v_lshlrev_b32_e32 v132, 4, v132
	global_load_dwordx4 v[136:139], v132, s[98:99] sc0 sc1
	v_add_u32_e32 v132, 0x2000, v132
	global_load_dwordx4 v[140:143], v132, s[98:99] sc0 sc1
	v_add_u32_e32 v132, 0x2000, v132
	global_load_dwordx4 v[144:147], v132, s[98:99] sc0 sc1
	v_add_u32_e32 v132, 0x2000, v132
	global_load_dwordx4 v[148:151], v132, s[98:99] sc0 sc1
	v_add_u32_e32 v132, 0x2000, v132
	global_load_dwordx4 v[152:155], v132, s[98:99] sc0 sc1
	v_add_u32_e32 v132, 0x2000, v132
	global_load_dwordx4 v[156:159], v132, s[98:99] sc0 sc1
	v_add_u32_e32 v132, 0x2000, v132
	global_load_dwordx4 v[160:163], v132, s[98:99] sc0 sc1
	v_add_u32_e32 v132, 0x2000, v132
	global_load_dwordx4 v[164:167], v132, s[98:99] sc0 sc1
	v_add_u32_e32 v132, 0x2000, v132
	s_waitcnt vmcnt(7)
	v_pk_add_f32 v[4:5], v[4:5], v[136:137]
	v_pk_add_f32 v[6:7], v[6:7], v[138:139]
	s_waitcnt vmcnt(6)
	v_pk_add_f32 v[8:9], v[8:9], v[140:141]
	v_pk_add_f32 v[10:11], v[10:11], v[142:143]
	s_waitcnt vmcnt(5)
	v_pk_add_f32 v[12:13], v[12:13], v[144:145]
	v_pk_add_f32 v[14:15], v[14:15], v[146:147]
	s_waitcnt vmcnt(4)
	v_pk_add_f32 v[16:17], v[16:17], v[148:149]
	v_pk_add_f32 v[18:19], v[18:19], v[150:151]
	s_waitcnt vmcnt(3)
	v_pk_add_f32 v[20:21], v[20:21], v[152:153]
	v_pk_add_f32 v[22:23], v[22:23], v[154:155]
	s_waitcnt vmcnt(2)
	v_pk_add_f32 v[24:25], v[24:25], v[156:157]
	v_pk_add_f32 v[26:27], v[26:27], v[158:159]
	s_waitcnt vmcnt(1)
	v_pk_add_f32 v[28:29], v[28:29], v[160:161]
	v_pk_add_f32 v[30:31], v[30:31], v[162:163]
	s_waitcnt vmcnt(0)
	v_pk_add_f32 v[32:33], v[32:33], v[164:165]
	v_pk_add_f32 v[34:35], v[34:35], v[166:167]
	global_load_dwordx4 v[136:139], v132, s[98:99] sc0 sc1
	v_add_u32_e32 v132, 0x2000, v132
	global_load_dwordx4 v[140:143], v132, s[98:99] sc0 sc1
	v_add_u32_e32 v132, 0x2000, v132
	global_load_dwordx4 v[144:147], v132, s[98:99] sc0 sc1
	v_add_u32_e32 v132, 0x2000, v132
	global_load_dwordx4 v[148:151], v132, s[98:99] sc0 sc1
	v_add_u32_e32 v132, 0x2000, v132
	global_load_dwordx4 v[152:155], v132, s[98:99] sc0 sc1
	v_add_u32_e32 v132, 0x2000, v132
	global_load_dwordx4 v[156:159], v132, s[98:99] sc0 sc1
	v_add_u32_e32 v132, 0x2000, v132
	global_load_dwordx4 v[160:163], v132, s[98:99] sc0 sc1
	v_add_u32_e32 v132, 0x2000, v132
	global_load_dwordx4 v[164:167], v132, s[98:99] sc0 sc1
	v_add_u32_e32 v132, 0x2000, v132
	s_waitcnt vmcnt(7)
; template <class Epi, int LDA, int LDB, int KK>
; __device__ __forceinline__ void gemm_phase(int wv, LAS unsigned char* lds, const Gemm g, const StaticOrder& S, const Epi& E) {
;     ...
;         for (int seg = 0, t = 0; seg < Epi::NSEG; ++seg) {
;           const int tend = Epi::HAS_MID ? (seg == 0 ? Epi::MID1 : (seg == 1 ? Epi::MID2 : nt)) : nt;
;           for (; t < tend; t += 2) {
	v_pk_add_f32 v[36:37], v[36:37], v[136:137]
	v_pk_add_f32 v[38:39], v[38:39], v[138:139]
	s_waitcnt vmcnt(6)
	v_pk_add_f32 v[40:41], v[40:41], v[140:141]
	v_pk_add_f32 v[42:43], v[42:43], v[142:143]
	s_waitcnt vmcnt(5)
	v_pk_add_f32 v[44:45], v[44:45], v[144:145]
	v_pk_add_f32 v[46:47], v[46:47], v[146:147]
	s_waitcnt vmcnt(4)
	v_pk_add_f32 v[48:49], v[48:49], v[148:149]
	v_pk_add_f32 v[50:51], v[50:51], v[150:151]
	s_waitcnt vmcnt(3)
	v_pk_add_f32 v[52:53], v[52:53], v[152:153]
	v_pk_add_f32 v[54:55], v[54:55], v[154:155]
	s_waitcnt vmcnt(2)
	v_pk_add_f32 v[56:57], v[56:57], v[156:157]
	v_pk_add_f32 v[58:59], v[58:59], v[158:159]
	s_waitcnt vmcnt(1)
	v_pk_add_f32 v[60:61], v[60:61], v[160:161]
	v_pk_add_f32 v[62:63], v[62:63], v[162:163]
	s_waitcnt vmcnt(0)
	v_pk_add_f32 v[64:65], v[64:65], v[164:165]
	v_pk_add_f32 v[66:67], v[66:67], v[166:167]
	global_load_dwordx4 v[136:139], v132, s[98:99] sc0 sc1
	v_add_u32_e32 v132, 0x2000, v132
	global_load_dwordx4 v[140:143], v132, s[98:99] sc0 sc1
	v_add_u32_e32 v132, 0x2000, v132
	global_load_dwordx4 v[144:147], v132, s[98:99] sc0 sc1
	v_add_u32_e32 v132, 0x2000, v132
	global_load_dwordx4 v[148:151], v132, s[98:99] sc0 sc1
	v_add_u32_e32 v132, 0x2000, v132
	global_load_dwordx4 v[152:155], v132, s[98:99] sc0 sc1
	v_add_u32_e32 v132, 0x2000, v132
	global_load_dwordx4 v[156:159], v132, s[98:99] sc0 sc1
	v_add_u32_e32 v132, 0x2000, v132
	global_load_dwordx4 v[160:163], v132, s[98:99] sc0 sc1
	v_add_u32_e32 v132, 0x2000, v132
	global_load_dwordx4 v[164:167], v132, s[98:99] sc0 sc1
	v_add_u32_e32 v132, 0x2000, v132
	s_waitcnt vmcnt(7)
	v_pk_add_f32 v[68:69], v[68:69], v[136:137]
	v_pk_add_f32 v[70:71], v[70:71], v[138:139]
	s_waitcnt vmcnt(6)
	v_pk_add_f32 v[72:73], v[72:73], v[140:141]
	v_pk_add_f32 v[74:75], v[74:75], v[142:143]
	s_waitcnt vmcnt(5)
	v_pk_add_f32 v[76:77], v[76:77], v[144:145]
	v_pk_add_f32 v[78:79], v[78:79], v[146:147]
	s_waitcnt vmcnt(4)
	v_pk_add_f32 v[80:81], v[80:81], v[148:149]
	v_pk_add_f32 v[82:83], v[82:83], v[150:151]
	s_waitcnt vmcnt(3)
	v_pk_add_f32 v[84:85], v[84:85], v[152:153]
	v_pk_add_f32 v[86:87], v[86:87], v[154:155]
	s_waitcnt vmcnt(2)
	v_pk_add_f32 v[88:89], v[88:89], v[156:157]
	v_pk_add_f32 v[90:91], v[90:91], v[158:159]
	s_waitcnt vmcnt(1)
	v_pk_add_f32 v[92:93], v[92:93], v[160:161]
	v_pk_add_f32 v[94:95], v[94:95], v[162:163]
	s_waitcnt vmcnt(0)
	v_pk_add_f32 v[96:97], v[96:97], v[164:165]
	v_pk_add_f32 v[98:99], v[98:99], v[166:167]
	global_load_dwordx4 v[136:139], v132, s[98:99] sc0 sc1
	v_add_u32_e32 v132, 0x2000, v132
	global_load_dwordx4 v[140:143], v132, s[98:99] sc0 sc1
	v_add_u32_e32 v132, 0x2000, v132
	global_load_dwordx4 v[144:147], v132, s[98:99] sc0 sc1
	v_add_u32_e32 v132, 0x2000, v132
	global_load_dwordx4 v[148:151], v132, s[98:99] sc0 sc1
	v_add_u32_e32 v132, 0x2000, v132
	global_load_dwordx4 v[152:155], v132, s[98:99] sc0 sc1
	v_add_u32_e32 v132, 0x2000, v132
	global_load_dwordx4 v[156:159], v132, s[98:99] sc0 sc1
	v_add_u32_e32 v132, 0x2000, v132
	global_load_dwordx4 v[160:163], v132, s[98:99] sc0 sc1
	v_add_u32_e32 v132, 0x2000, v132
	global_load_dwordx4 v[164:167], v132, s[98:99] sc0 sc1
	s_waitcnt vmcnt(7)
	v_pk_add_f32 v[100:101], v[100:101], v[136:137]
	v_pk_add_f32 v[102:103], v[102:103], v[138:139]
	s_waitcnt vmcnt(6)
	v_pk_add_f32 v[104:105], v[104:105], v[140:141]
	v_pk_add_f32 v[106:107], v[106:107], v[142:143]
	s_waitcnt vmcnt(5)
	v_pk_add_f32 v[108:109], v[108:109], v[144:145]
	v_pk_add_f32 v[110:111], v[110:111], v[146:147]
	s_waitcnt vmcnt(4)
	v_pk_add_f32 v[112:113], v[112:113], v[148:149]
	v_pk_add_f32 v[114:115], v[114:115], v[150:151]
	s_waitcnt vmcnt(3)
	v_pk_add_f32 v[116:117], v[116:117], v[152:153]
	v_pk_add_f32 v[118:119], v[118:119], v[154:155]
	s_waitcnt vmcnt(2)
	v_pk_add_f32 v[120:121], v[120:121], v[156:157]
	v_pk_add_f32 v[122:123], v[122:123], v[158:159]
	s_waitcnt vmcnt(1)
	v_pk_add_f32 v[124:125], v[124:125], v[160:161]
	v_pk_add_f32 v[126:127], v[126:127], v[162:163]
	s_waitcnt vmcnt(0)
	v_pk_add_f32 v[128:129], v[128:129], v[164:165]
	v_pk_add_f32 v[130:131], v[130:131], v[166:167]
.Lmt_sd:
	s_mov_b32 s22, s46
.Lmt_no:
	s_cmp_ge_i32 s22, s46
	s_cbranch_scc1 .LBB0_524
	s_ashr_i32 s23, s22, 31
	s_lshl_b64 s[24:25], s[22:23], 7
	s_add_u32 s23, s45, s24
	s_addc_u32 s47, s70, s25
	s_add_u32 s55, s71, s24
	s_addc_u32 s56, s73, s25
	v_add_u32_e32 v0, 0x10000, v216
	ds_read_b128 v[132:135], v0 offset:0
	ds_read_b128 v[136:139], v0 offset:2048
	ds_read_b128 v[140:143], v0 offset:16384
	ds_read_b128 v[144:147], v0 offset:18432
	ds_read_b128 v[148:151], v218 offset:0
	ds_read_b128 v[152:155], v218 offset:2048
	ds_read_b128 v[156:159], v218 offset:4096
	ds_read_b128 v[160:163], v218 offset:6144

; __device__ __forceinline__ float lo16(unsigned w) { return __uint_as_float(w << 16); }
; __device__ __forceinline__ float hi16(unsigned w) { return __uint_as_float(w & 0xffff0000u); }
;     __device__ __forceinline__ void mid(AccT& acc, const pg8::Unit& u, int which, int wr, int wc, int fr, int fq) const {
;         int row0 = u.pm * 256 + wr * 64 + fr; asm volatile("" : "+v"(row0)); const int cb = u.pn * 256 + wc * 32 + 8 * fq; const int onum = which * 2048, oden = onum + 2048;
; #pragma unroll
;         for (int ai = 0; ai < 2; ++ai) {
;             u32x4 gn[4][2], gd[4][2];
; #pragma unroll
;             for (int m = 0; m < 4; ++m)
; #pragma unroll
;                 for (int bj = 0; bj < 2; ++bj) { const bf16_t* zr = zG + (size_t)(row0 + ai * 128 + m * 16) * NZG + cb + bj * 128; gn[m][bj] = *(const u32x4*)(zr + onum); gd[m][bj] = *(const u32x4*)(zr + oden); }
; #pragma unroll
;             for (int m = 0; m < 4; ++m)
; #pragma unroll
;                 for (int bj = 0; bj < 2; ++bj)
; #pragma unroll
;                     for (int q = 0; q < 4; ++q) {
;                         const float r0 = (1.0f + __expf(-lo16(gd[m][bj][q]))) * __builtin_amdgcn_rcpf(1.0f + __expf(-lo16(gn[m][bj][q]))), r1 = (1.0f + __expf(-hi16(gd[m][bj][q]))) * __builtin_amdgcn_rcpf(1.0f + __expf(-hi16(gn[m][bj][q])));
;                         acc[ai][bj][m][q >> 1][(q & 1) * 2] *= r0; acc[ai][bj][m][q >> 1][(q & 1) * 2 + 1] *= r1;
;                     }
;         }
;     }
.LBB0_524:
	s_cmp_gt_u32 s100, 1
	s_cbranch_scc1 .Lmt_prod
	s_cmp_eq_u32 s74, 2
	s_cbranch_scc1 .LBB0_520
	s_lshl_b32 s56, s74, 12
	v_mov_b32_e32 v2, v210
	v_lshl_add_u64 v[0:1], v[214:215], 0, s[56:57]
	s_nop 0
	v_mad_i64_i32 v[132:133], s[24:25], v2, s61, v[0:1]
	v_add_co_u32_e32 v134, vcc, 0x1000, v132
	global_load_dwordx4 v[188:191], v[132:133], off
	s_nop 0
	v_addc_co_u32_e32 v135, vcc, 0, v133, vcc
	global_load_dwordx4 v[192:195], v[134:135], off
	global_load_dwordx4 v[180:183], v[132:133], off offset:256
	global_load_dwordx4 v[184:187], v[134:135], off offset:256
	v_add_u32_e32 v132, 16, v2
	v_mad_i64_i32 v[132:133], s[24:25], v132, s61, v[0:1]
	global_load_dwordx4 v[172:175], v[132:133], off
	v_add_co_u32_e32 v134, vcc, 0x1000, v132
	s_waitcnt vmcnt(0)
	v_lshlrev_b32_e32 v211, 16, v192
	v_mul_f32_e32 v211, 0xbfb8aa3b, v211
	v_addc_co_u32_e32 v135, vcc, 0, v133, vcc
	v_exp_f32_e32 v230, v211
	v_lshlrev_b32_e32 v211, 16, v188
	v_and_b32_e32 v188, 0xffff0000, v188
	global_load_dwordx4 v[176:179], v[134:135], off
	global_load_dwordx4 v[164:167], v[132:133], off offset:256
	global_load_dwordx4 v[168:171], v[134:135], off offset:256
	v_mul_f32_e32 v188, 0xbfb8aa3b, v188
	v_exp_f32_e32 v188, v188
	v_and_b32_e32 v192, 0xffff0000, v192
	v_mul_f32_e32 v192, 0xbfb8aa3b, v192
	v_exp_f32_e32 v231, v192
	v_add_f32_e32 v188, 1.0, v188
	v_rcp_f32_e32 v233, v188
	v_lshlrev_b32_e32 v188, 16, v193
	v_mul_f32_e32 v188, 0xbfb8aa3b, v188
	v_exp_f32_e32 v192, v188
	v_lshlrev_b32_e32 v188, 16, v189
	v_and_b32_e32 v189, 0xffff0000, v189
	v_mul_f32_e32 v188, 0xbfb8aa3b, v188
	v_mul_f32_e32 v189, 0xbfb8aa3b, v189
	v_exp_f32_e32 v188, v188
	v_exp_f32_e32 v189, v189
	v_and_b32_e32 v193, 0xffff0000, v193
	v_mul_f32_e32 v193, 0xbfb8aa3b, v193
	v_add_f32_e32 v188, 1.0, v188
	v_exp_f32_e32 v193, v193
	v_add_f32_e32 v189, 1.0, v189
	v_rcp_f32_e32 v188, v188
	v_rcp_f32_e32 v189, v189
	v_pk_add_f32 v[192:193], v[192:193], 1.0 op_sel_hi:[1,0]
	v_add_u32_e32 v132, 32, v2
	v_mad_i64_i32 v[132:133], s[24:25], v132, s61, v[0:1]
	v_pk_mul_f32 v[188:189], v[192:193], v[188:189]
	global_load_dwordx4 v[156:159], v[132:133], off
	v_pk_mul_f32 v[130:131], v[130:131], v[188:189]
	v_lshlrev_b32_e32 v189, 16, v190
	v_mul_f32_e32 v189, 0xbfb8aa3b, v189
	v_and_b32_e32 v190, 0xffff0000, v190
	v_exp_f32_e32 v189, v189
	v_mul_f32_e32 v190, 0xbfb8aa3b, v190
	v_exp_f32_e32 v190, v190
	v_lshlrev_b32_e32 v188, 16, v194
	v_add_f32_e32 v189, 1.0, v189
	v_rcp_f32_e32 v192, v189
	v_and_b32_e32 v189, 0xffff0000, v194
	v_add_f32_e32 v190, 1.0, v190
	v_mul_f32_e32 v188, 0xbfb8aa3b, v188
	v_mul_f32_e32 v189, 0xbfb8aa3b, v189
	v_rcp_f32_e32 v193, v190
	v_lshlrev_b32_e32 v190, 16, v195
	v_exp_f32_e32 v188, v188
	v_exp_f32_e32 v189, v189
	v_mul_f32_e32 v190, 0xbfb8aa3b, v190
	v_exp_f32_e32 v194, v190
	v_lshlrev_b32_e32 v190, 16, v191
	v_and_b32_e32 v191, 0xffff0000, v191
	v_mul_f32_e32 v190, 0xbfb8aa3b, v190
	v_mul_f32_e32 v191, 0xbfb8aa3b, v191
	v_exp_f32_e32 v190, v190
	v_exp_f32_e32 v191, v191
	v_pk_add_f32 v[188:189], v[188:189], 1.0 op_sel_hi:[1,0]
	v_and_b32_e32 v195, 0xffff0000, v195
	v_pk_mul_f32 v[188:189], v[188:189], v[192:193]
	v_mul_f32_e32 v195, 0xbfb8aa3b, v195
	v_pk_mul_f32 v[124:125], v[124:125], v[188:189]
	v_lshlrev_b32_e32 v189, 16, v180
	v_and_b32_e32 v180, 0xffff0000, v180
	v_add_f32_e32 v190, 1.0, v190
	v_exp_f32_e32 v195, v195
	v_add_f32_e32 v191, 1.0, v191
	v_mul_f32_e32 v180, 0xbfb8aa3b, v180
	v_rcp_f32_e32 v190, v190
	v_rcp_f32_e32 v191, v191
	v_exp_f32_e32 v180, v180
	v_mul_f32_e32 v189, 0xbfb8aa3b, v189
	v_exp_f32_e32 v189, v189
	v_pk_add_f32 v[194:195], v[194:195], 1.0 op_sel_hi:[1,0]
	v_add_f32_e32 v180, 1.0, v180
	v_pk_mul_f32 v[190:191], v[194:195], v[190:191]
	v_lshlrev_b32_e32 v188, 16, v184
	v_pk_mul_f32 v[126:127], v[126:127], v[190:191]
	v_and_b32_e32 v184, 0xffff0000, v184
	v_rcp_f32_e32 v191, v180
	v_lshlrev_b32_e32 v180, 16, v185
	v_add_f32_e32 v189, 1.0, v189
	v_mul_f32_e32 v184, 0xbfb8aa3b, v184
	v_mul_f32_e32 v180, 0xbfb8aa3b, v180
	v_rcp_f32_e32 v190, v189
	v_exp_f32_e32 v189, v184
	v_exp_f32_e32 v184, v180
	v_lshlrev_b32_e32 v180, 16, v181
	v_and_b32_e32 v181, 0xffff0000, v181
	v_mul_f32_e32 v180, 0xbfb8aa3b, v180
	v_mul_f32_e32 v181, 0xbfb8aa3b, v181
	v_exp_f32_e32 v180, v180
	v_exp_f32_e32 v181, v181
	v_and_b32_e32 v185, 0xffff0000, v185
	v_mul_f32_e32 v185, 0xbfb8aa3b, v185
	v_add_f32_e32 v180, 1.0, v180
	v_exp_f32_e32 v185, v185
	v_add_f32_e32 v181, 1.0, v181
	v_rcp_f32_e32 v180, v180
	v_rcp_f32_e32 v181, v181
	v_pk_add_f32 v[184:185], v[184:185], 1.0 op_sel_hi:[1,0]
	v_add_co_u32_e32 v134, vcc, 0x1000, v132
	v_pk_mul_f32 v[180:181], v[184:185], v[180:181]
	s_nop 0
	v_addc_co_u32_e32 v135, vcc, 0, v133, vcc
	v_pk_mul_f32 v[122:123], v[122:123], v[180:181]
	v_lshlrev_b32_e32 v181, 16, v182
	v_mul_f32_e32 v181, 0xbfb8aa3b, v181
	v_and_b32_e32 v182, 0xffff0000, v182
	v_exp_f32_e32 v181, v181
	v_mul_f32_e32 v182, 0xbfb8aa3b, v182
	v_exp_f32_e32 v182, v182
	v_lshlrev_b32_e32 v180, 16, v186
	v_add_f32_e32 v181, 1.0, v181
	v_rcp_f32_e32 v184, v181
	v_and_b32_e32 v181, 0xffff0000, v186
	v_add_f32_e32 v182, 1.0, v182
	v_mul_f32_e32 v180, 0xbfb8aa3b, v180
	v_mul_f32_e32 v181, 0xbfb8aa3b, v181
	v_rcp_f32_e32 v185, v182
	v_lshlrev_b32_e32 v182, 16, v187
	v_exp_f32_e32 v180, v180
	v_exp_f32_e32 v181, v181
	v_mul_f32_e32 v182, 0xbfb8aa3b, v182
	v_exp_f32_e32 v186, v182
	v_lshlrev_b32_e32 v182, 16, v183
	v_and_b32_e32 v183, 0xffff0000, v183
	v_mul_f32_e32 v182, 0xbfb8aa3b, v182
	v_mul_f32_e32 v183, 0xbfb8aa3b, v183
	v_exp_f32_e32 v182, v182
	v_exp_f32_e32 v183, v183
	v_pk_add_f32 v[180:181], v[180:181], 1.0 op_sel_hi:[1,0]
	v_and_b32_e32 v187, 0xffff0000, v187
	v_pk_mul_f32 v[180:181], v[180:181], v[184:185]
	v_mul_f32_e32 v187, 0xbfb8aa3b, v187
	v_pk_mul_f32 v[116:117], v[116:117], v[180:181]
	v_lshlrev_b32_e32 v181, 16, v172
	v_and_b32_e32 v172, 0xffff0000, v172
	global_load_dwordx4 v[160:163], v[134:135], off
	global_load_dwordx4 v[148:151], v[132:133], off offset:256
	global_load_dwordx4 v[152:155], v[134:135], off offset:256
	v_add_f32_e32 v182, 1.0, v182
	v_exp_f32_e32 v187, v187
	v_add_f32_e32 v183, 1.0, v183
	v_mul_f32_e32 v172, 0xbfb8aa3b, v172
	v_rcp_f32_e32 v182, v182
	v_rcp_f32_e32 v183, v183
	v_exp_f32_e32 v172, v172
	v_mul_f32_e32 v181, 0xbfb8aa3b, v181
	v_exp_f32_e32 v181, v181
	v_pk_add_f32 v[186:187], v[186:187], 1.0 op_sel_hi:[1,0]
	v_add_f32_e32 v172, 1.0, v172
	v_pk_mul_f32 v[182:183], v[186:187], v[182:183]
	s_waitcnt vmcnt(0)
; __device__ __forceinline__ float lo16(unsigned w) { return __uint_as_float(w << 16); }
; __device__ __forceinline__ float hi16(unsigned w) { return __uint_as_float(w & 0xffff0000u); }
;     __device__ __forceinline__ void mid(AccT& acc, const pg8::Unit& u, int which, int wr, int wc, int fr, int fq) const {
;     ...
;             for (int m = 0; m < 4; ++m)
; #pragma unroll
;                 for (int bj = 0; bj < 2; ++bj) { const bf16_t* zr = zG + (size_t)(row0 + ai * 128 + m * 16) * NZG + cb + bj * 128; gn[m][bj] = *(const u32x4*)(zr + onum); gd[m][bj] = *(const u32x4*)(zr + oden); }
; #pragma unroll
;             for (int m = 0; m < 4; ++m)
; #pragma unroll
;                 for (int bj = 0; bj < 2; ++bj)
; #pragma unroll
;                     for (int q = 0; q < 4; ++q) {
;                         const float r0 = (1.0f + __expf(-lo16(gd[m][bj][q]))) * __builtin_amdgcn_rcpf(1.0f + __expf(-lo16(gn[m][bj][q]))), r1 = (1.0f + __expf(-hi16(gd[m][bj][q]))) * __builtin_amdgcn_rcpf(1.0f + __expf(-hi16(gn[m][bj][q])));
;                         acc[ai][bj][m][q >> 1][(q & 1) * 2] *= r0; acc[ai][bj][m][q >> 1][(q & 1) * 2 + 1] *= r1;
;                     }
	v_lshlrev_b32_e32 v180, 16, v176
	v_pk_mul_f32 v[118:119], v[118:119], v[182:183]
	v_and_b32_e32 v176, 0xffff0000, v176
	v_rcp_f32_e32 v183, v172
	v_lshlrev_b32_e32 v172, 16, v177
	v_add_f32_e32 v181, 1.0, v181
	v_mul_f32_e32 v176, 0xbfb8aa3b, v176
	v_mul_f32_e32 v172, 0xbfb8aa3b, v172
	v_rcp_f32_e32 v182, v181
	v_exp_f32_e32 v181, v176
	v_exp_f32_e32 v176, v172
	v_lshlrev_b32_e32 v172, 16, v173
	v_and_b32_e32 v173, 0xffff0000, v173
	v_mul_f32_e32 v172, 0xbfb8aa3b, v172
	v_mul_f32_e32 v173, 0xbfb8aa3b, v173
	v_exp_f32_e32 v172, v172
	v_exp_f32_e32 v173, v173
	v_and_b32_e32 v177, 0xffff0000, v177
	v_mul_f32_e32 v177, 0xbfb8aa3b, v177
	v_add_f32_e32 v172, 1.0, v172
	v_exp_f32_e32 v177, v177
	v_add_f32_e32 v173, 1.0, v173
	v_rcp_f32_e32 v172, v172
	v_rcp_f32_e32 v173, v173
	v_pk_add_f32 v[176:177], v[176:177], 1.0 op_sel_hi:[1,0]
	v_add_u32_e32 v132, 48, v2
	v_mad_i64_i32 v[132:133], s[24:25], v132, s61, v[0:1]
	v_pk_mul_f32 v[172:173], v[176:177], v[172:173]
	global_load_dwordx4 v[140:143], v[132:133], off
	v_pk_mul_f32 v[114:115], v[114:115], v[172:173]
	v_lshlrev_b32_e32 v173, 16, v174
	v_mul_f32_e32 v173, 0xbfb8aa3b, v173
	v_and_b32_e32 v174, 0xffff0000, v174
	v_exp_f32_e32 v173, v173
	v_mul_f32_e32 v174, 0xbfb8aa3b, v174
	v_exp_f32_e32 v174, v174
	v_lshlrev_b32_e32 v172, 16, v178
	v_add_f32_e32 v173, 1.0, v173
	v_rcp_f32_e32 v176, v173
	v_and_b32_e32 v173, 0xffff0000, v178
	v_add_f32_e32 v174, 1.0, v174
	v_mul_f32_e32 v172, 0xbfb8aa3b, v172
	v_mul_f32_e32 v173, 0xbfb8aa3b, v173
	v_rcp_f32_e32 v177, v174
	v_lshlrev_b32_e32 v174, 16, v179
	v_exp_f32_e32 v172, v172
	v_exp_f32_e32 v173, v173
	v_mul_f32_e32 v174, 0xbfb8aa3b, v174
	v_exp_f32_e32 v178, v174
	v_lshlrev_b32_e32 v174, 16, v175
	v_and_b32_e32 v175, 0xffff0000, v175
	v_mul_f32_e32 v174, 0xbfb8aa3b, v174
	v_mul_f32_e32 v175, 0xbfb8aa3b, v175
	v_exp_f32_e32 v174, v174
	v_exp_f32_e32 v175, v175
	v_pk_add_f32 v[172:173], v[172:173], 1.0 op_sel_hi:[1,0]
	v_and_b32_e32 v179, 0xffff0000, v179
	v_pk_mul_f32 v[172:173], v[172:173], v[176:177]
	v_mul_f32_e32 v179, 0xbfb8aa3b, v179
	v_pk_mul_f32 v[108:109], v[108:109], v[172:173]
	v_lshlrev_b32_e32 v173, 16, v164
	v_and_b32_e32 v164, 0xffff0000, v164
	v_add_f32_e32 v174, 1.0, v174
	v_exp_f32_e32 v179, v179
	v_add_f32_e32 v175, 1.0, v175
	v_mul_f32_e32 v164, 0xbfb8aa3b, v164
	v_rcp_f32_e32 v174, v174
	v_rcp_f32_e32 v175, v175
	v_exp_f32_e32 v164, v164
	v_mul_f32_e32 v173, 0xbfb8aa3b, v173
	v_exp_f32_e32 v173, v173
	v_pk_add_f32 v[178:179], v[178:179], 1.0 op_sel_hi:[1,0]
	v_add_f32_e32 v164, 1.0, v164
	v_pk_mul_f32 v[174:175], v[178:179], v[174:175]
	v_lshlrev_b32_e32 v172, 16, v168
	v_pk_mul_f32 v[110:111], v[110:111], v[174:175]
	v_and_b32_e32 v168, 0xffff0000, v168
	v_rcp_f32_e32 v175, v164
	v_lshlrev_b32_e32 v164, 16, v169
	v_add_f32_e32 v173, 1.0, v173
	v_mul_f32_e32 v168, 0xbfb8aa3b, v168
	v_mul_f32_e32 v164, 0xbfb8aa3b, v164
	v_rcp_f32_e32 v174, v173
	v_exp_f32_e32 v173, v168
	v_exp_f32_e32 v168, v164
	v_lshlrev_b32_e32 v164, 16, v165
	v_and_b32_e32 v165, 0xffff0000, v165
	v_mul_f32_e32 v164, 0xbfb8aa3b, v164
	v_mul_f32_e32 v165, 0xbfb8aa3b, v165
	v_exp_f32_e32 v164, v164
	v_exp_f32_e32 v165, v165
	v_and_b32_e32 v169, 0xffff0000, v169
	v_mul_f32_e32 v169, 0xbfb8aa3b, v169
	v_add_f32_e32 v164, 1.0, v164
	v_exp_f32_e32 v169, v169
	v_add_f32_e32 v165, 1.0, v165
	v_rcp_f32_e32 v164, v164
	v_rcp_f32_e32 v165, v165
	v_pk_add_f32 v[168:169], v[168:169], 1.0 op_sel_hi:[1,0]
	v_add_co_u32_e32 v136, vcc, 0x1000, v132
	v_pk_mul_f32 v[164:165], v[168:169], v[164:165]
	s_nop 0
	v_addc_co_u32_e32 v137, vcc, 0, v133, vcc
	v_pk_mul_f32 v[106:107], v[106:107], v[164:165]
	v_lshlrev_b32_e32 v165, 16, v166
	v_mul_f32_e32 v165, 0xbfb8aa3b, v165
	v_and_b32_e32 v166, 0xffff0000, v166
	v_exp_f32_e32 v165, v165
	v_mul_f32_e32 v166, 0xbfb8aa3b, v166
	v_exp_f32_e32 v166, v166
	v_lshlrev_b32_e32 v164, 16, v170
	v_add_f32_e32 v165, 1.0, v165
	v_rcp_f32_e32 v168, v165
	v_and_b32_e32 v165, 0xffff0000, v170
	v_add_f32_e32 v166, 1.0, v166
	v_mul_f32_e32 v164, 0xbfb8aa3b, v164
	v_mul_f32_e32 v165, 0xbfb8aa3b, v165
	v_rcp_f32_e32 v169, v166
	v_lshlrev_b32_e32 v166, 16, v171
	v_exp_f32_e32 v164, v164
	v_exp_f32_e32 v165, v165
	v_mul_f32_e32 v166, 0xbfb8aa3b, v166
	v_exp_f32_e32 v170, v166
	v_lshlrev_b32_e32 v166, 16, v167
	v_and_b32_e32 v167, 0xffff0000, v167
	v_mul_f32_e32 v166, 0xbfb8aa3b, v166
	v_mul_f32_e32 v167, 0xbfb8aa3b, v167
	v_exp_f32_e32 v166, v166
	v_exp_f32_e32 v167, v167
	v_pk_add_f32 v[164:165], v[164:165], 1.0 op_sel_hi:[1,0]
	v_and_b32_e32 v171, 0xffff0000, v171
	v_pk_mul_f32 v[164:165], v[164:165], v[168:169]
	v_mul_f32_e32 v171, 0xbfb8aa3b, v171
	v_pk_mul_f32 v[100:101], v[100:101], v[164:165]
	v_lshlrev_b32_e32 v165, 16, v156
	v_and_b32_e32 v156, 0xffff0000, v156
	global_load_dwordx4 v[144:147], v[136:137], off
	s_nop 0
	global_load_dwordx4 v[132:135], v[132:133], off offset:256
	s_nop 0
	global_load_dwordx4 v[136:139], v[136:137], off offset:256
	v_add_f32_e32 v166, 1.0, v166
	v_exp_f32_e32 v171, v171
	v_add_f32_e32 v167, 1.0, v167
	v_mul_f32_e32 v156, 0xbfb8aa3b, v156
	v_rcp_f32_e32 v166, v166
	v_rcp_f32_e32 v167, v167
	v_exp_f32_e32 v156, v156
	v_mul_f32_e32 v165, 0xbfb8aa3b, v165
	v_exp_f32_e32 v165, v165
	v_pk_add_f32 v[170:171], v[170:171], 1.0 op_sel_hi:[1,0]
	v_add_f32_e32 v156, 1.0, v156
	v_pk_mul_f32 v[166:167], v[170:171], v[166:167]
	v_lshlrev_b32_e32 v164, 16, v160
	v_pk_mul_f32 v[102:103], v[102:103], v[166:167]
	v_and_b32_e32 v160, 0xffff0000, v160
	v_rcp_f32_e32 v167, v156
	v_lshlrev_b32_e32 v156, 16, v161
	v_add_f32_e32 v165, 1.0, v165
	v_mul_f32_e32 v160, 0xbfb8aa3b, v160
	v_mul_f32_e32 v156, 0xbfb8aa3b, v156
	v_rcp_f32_e32 v166, v165
; __device__ __forceinline__ float lo16(unsigned w) { return __uint_as_float(w << 16); }
; __device__ __forceinline__ float hi16(unsigned w) { return __uint_as_float(w & 0xffff0000u); }
;     __device__ __forceinline__ void mid(AccT& acc, const pg8::Unit& u, int which, int wr, int wc, int fr, int fq) const {
;     ...
;             for (int m = 0; m < 4; ++m)
; #pragma unroll
;                 for (int bj = 0; bj < 2; ++bj) { const bf16_t* zr = zG + (size_t)(row0 + ai * 128 + m * 16) * NZG + cb + bj * 128; gn[m][bj] = *(const u32x4*)(zr + onum); gd[m][bj] = *(const u32x4*)(zr + oden); }
; #pragma unroll
;             for (int m = 0; m < 4; ++m)
; #pragma unroll
;                 for (int bj = 0; bj < 2; ++bj)
; #pragma unroll
;                     for (int q = 0; q < 4; ++q) {
;                         const float r0 = (1.0f + __expf(-lo16(gd[m][bj][q]))) * __builtin_amdgcn_rcpf(1.0f + __expf(-lo16(gn[m][bj][q]))), r1 = (1.0f + __expf(-hi16(gd[m][bj][q]))) * __builtin_amdgcn_rcpf(1.0f + __expf(-hi16(gn[m][bj][q])));
;                         acc[ai][bj][m][q >> 1][(q & 1) * 2] *= r0; acc[ai][bj][m][q >> 1][(q & 1) * 2 + 1] *= r1;
;                     }
	v_exp_f32_e32 v165, v160
	v_exp_f32_e32 v160, v156
	v_lshlrev_b32_e32 v156, 16, v157
	v_and_b32_e32 v157, 0xffff0000, v157
	v_mul_f32_e32 v156, 0xbfb8aa3b, v156
	v_mul_f32_e32 v157, 0xbfb8aa3b, v157
	v_exp_f32_e32 v156, v156
	v_exp_f32_e32 v157, v157
	v_and_b32_e32 v161, 0xffff0000, v161
	v_mul_f32_e32 v161, 0xbfb8aa3b, v161
	v_add_f32_e32 v156, 1.0, v156
	v_exp_f32_e32 v161, v161
	v_add_f32_e32 v157, 1.0, v157
	v_rcp_f32_e32 v156, v156
	v_rcp_f32_e32 v157, v157
	v_pk_add_f32 v[160:161], v[160:161], 1.0 op_sel_hi:[1,0]
	v_mul_f32_e32 v188, 0xbfb8aa3b, v188
	v_exp_f32_e32 v188, v188
	v_pk_mul_f32 v[156:157], v[160:161], v[156:157]
	v_mul_f32_e32 v180, 0xbfb8aa3b, v180
	v_pk_mul_f32 v[98:99], v[98:99], v[156:157]
	v_lshlrev_b32_e32 v157, 16, v158
	v_mul_f32_e32 v157, 0xbfb8aa3b, v157
	v_and_b32_e32 v158, 0xffff0000, v158
	v_exp_f32_e32 v157, v157
	v_mul_f32_e32 v158, 0xbfb8aa3b, v158
	v_exp_f32_e32 v158, v158
	v_lshlrev_b32_e32 v156, 16, v162
	v_add_f32_e32 v157, 1.0, v157
	v_rcp_f32_e32 v160, v157
	v_and_b32_e32 v157, 0xffff0000, v162
	v_add_f32_e32 v158, 1.0, v158
	v_mul_f32_e32 v156, 0xbfb8aa3b, v156
	v_mul_f32_e32 v157, 0xbfb8aa3b, v157
	v_rcp_f32_e32 v161, v158
	v_lshlrev_b32_e32 v158, 16, v163
	v_exp_f32_e32 v156, v156
	v_exp_f32_e32 v157, v157
	v_mul_f32_e32 v158, 0xbfb8aa3b, v158
	v_exp_f32_e32 v162, v158
	v_lshlrev_b32_e32 v158, 16, v159
	v_and_b32_e32 v159, 0xffff0000, v159
	v_mul_f32_e32 v158, 0xbfb8aa3b, v158
	v_mul_f32_e32 v159, 0xbfb8aa3b, v159
	v_exp_f32_e32 v158, v158
	v_exp_f32_e32 v159, v159
	v_pk_add_f32 v[156:157], v[156:157], 1.0 op_sel_hi:[1,0]
	v_and_b32_e32 v163, 0xffff0000, v163
	v_pk_mul_f32 v[156:157], v[156:157], v[160:161]
	v_mul_f32_e32 v163, 0xbfb8aa3b, v163
	v_pk_mul_f32 v[92:93], v[92:93], v[156:157]
	v_lshlrev_b32_e32 v157, 16, v148
	v_and_b32_e32 v148, 0xffff0000, v148
	v_add_f32_e32 v158, 1.0, v158
	v_exp_f32_e32 v163, v163
	v_add_f32_e32 v159, 1.0, v159
	v_mul_f32_e32 v148, 0xbfb8aa3b, v148
	v_rcp_f32_e32 v158, v158
	v_rcp_f32_e32 v159, v159
	v_exp_f32_e32 v148, v148
	v_mul_f32_e32 v157, 0xbfb8aa3b, v157
	v_exp_f32_e32 v157, v157
	v_pk_add_f32 v[162:163], v[162:163], 1.0 op_sel_hi:[1,0]
	v_add_f32_e32 v148, 1.0, v148
	v_pk_mul_f32 v[158:159], v[162:163], v[158:159]
	v_lshlrev_b32_e32 v156, 16, v152
	v_pk_mul_f32 v[94:95], v[94:95], v[158:159]
	v_and_b32_e32 v152, 0xffff0000, v152
	v_rcp_f32_e32 v159, v148
	v_lshlrev_b32_e32 v148, 16, v153
	v_add_f32_e32 v157, 1.0, v157
	v_mul_f32_e32 v152, 0xbfb8aa3b, v152
	v_mul_f32_e32 v148, 0xbfb8aa3b, v148
	v_rcp_f32_e32 v158, v157
	v_exp_f32_e32 v157, v152
	v_exp_f32_e32 v152, v148
	v_lshlrev_b32_e32 v148, 16, v149
	v_and_b32_e32 v149, 0xffff0000, v149
	v_mul_f32_e32 v148, 0xbfb8aa3b, v148
	v_mul_f32_e32 v149, 0xbfb8aa3b, v149
	v_exp_f32_e32 v148, v148
	v_exp_f32_e32 v149, v149
	v_and_b32_e32 v153, 0xffff0000, v153
	v_mul_f32_e32 v153, 0xbfb8aa3b, v153
	v_add_f32_e32 v148, 1.0, v148
	v_exp_f32_e32 v153, v153
	v_add_f32_e32 v149, 1.0, v149
	v_rcp_f32_e32 v148, v148
	v_rcp_f32_e32 v149, v149
	v_pk_add_f32 v[152:153], v[152:153], 1.0 op_sel_hi:[1,0]
	v_pk_add_f32 v[188:189], v[188:189], 1.0 op_sel_hi:[1,0]
	v_exp_f32_e32 v180, v180
	v_pk_mul_f32 v[148:149], v[152:153], v[148:149]
	v_pk_mul_f32 v[188:189], v[188:189], v[190:191]
	v_pk_mul_f32 v[90:91], v[90:91], v[148:149]
	v_lshlrev_b32_e32 v149, 16, v150
	v_mul_f32_e32 v149, 0xbfb8aa3b, v149
	v_and_b32_e32 v150, 0xffff0000, v150
	v_exp_f32_e32 v149, v149
	v_mul_f32_e32 v150, 0xbfb8aa3b, v150
	v_exp_f32_e32 v150, v150
	v_lshlrev_b32_e32 v148, 16, v154
	v_add_f32_e32 v149, 1.0, v149
	v_rcp_f32_e32 v152, v149
	v_and_b32_e32 v149, 0xffff0000, v154
	v_add_f32_e32 v150, 1.0, v150
	v_mul_f32_e32 v148, 0xbfb8aa3b, v148
	v_mul_f32_e32 v149, 0xbfb8aa3b, v149
	v_rcp_f32_e32 v153, v150
	v_lshlrev_b32_e32 v150, 16, v155
	v_exp_f32_e32 v148, v148
	v_exp_f32_e32 v149, v149
	v_mul_f32_e32 v150, 0xbfb8aa3b, v150
	v_exp_f32_e32 v154, v150
	v_lshlrev_b32_e32 v150, 16, v151
	v_and_b32_e32 v151, 0xffff0000, v151
	v_mul_f32_e32 v150, 0xbfb8aa3b, v150
	v_mul_f32_e32 v151, 0xbfb8aa3b, v151
	v_exp_f32_e32 v150, v150
	v_exp_f32_e32 v151, v151
	v_pk_add_f32 v[148:149], v[148:149], 1.0 op_sel_hi:[1,0]
	v_and_b32_e32 v155, 0xffff0000, v155
	v_pk_mul_f32 v[148:149], v[148:149], v[152:153]
	v_mul_f32_e32 v155, 0xbfb8aa3b, v155
	v_pk_mul_f32 v[84:85], v[84:85], v[148:149]
	s_waitcnt vmcnt(0)
; __device__ __forceinline__ float lo16(unsigned w) { return __uint_as_float(w << 16); }
; __device__ __forceinline__ float hi16(unsigned w) { return __uint_as_float(w & 0xffff0000u); }
;     __device__ __forceinline__ void mid(AccT& acc, const pg8::Unit& u, int which, int wr, int wc, int fr, int fq) const {
;     ...
;             for (int m = 0; m < 4; ++m)
; #pragma unroll
;                 for (int bj = 0; bj < 2; ++bj) { const bf16_t* zr = zG + (size_t)(row0 + ai * 128 + m * 16) * NZG + cb + bj * 128; gn[m][bj] = *(const u32x4*)(zr + onum); gd[m][bj] = *(const u32x4*)(zr + oden); }
; #pragma unroll
;             for (int m = 0; m < 4; ++m)
; #pragma unroll
;                 for (int bj = 0; bj < 2; ++bj)
; #pragma unroll
;                     for (int q = 0; q < 4; ++q) {
;                         const float r0 = (1.0f + __expf(-lo16(gd[m][bj][q]))) * __builtin_amdgcn_rcpf(1.0f + __expf(-lo16(gn[m][bj][q]))), r1 = (1.0f + __expf(-hi16(gd[m][bj][q]))) * __builtin_amdgcn_rcpf(1.0f + __expf(-hi16(gn[m][bj][q])));
;                         acc[ai][bj][m][q >> 1][(q & 1) * 2] *= r0; acc[ai][bj][m][q >> 1][(q & 1) * 2 + 1] *= r1;
;                     }
	v_lshlrev_b32_e32 v149, 16, v140
	v_and_b32_e32 v140, 0xffff0000, v140
	v_add_f32_e32 v150, 1.0, v150
	v_exp_f32_e32 v155, v155
	v_add_f32_e32 v151, 1.0, v151
	v_mul_f32_e32 v140, 0xbfb8aa3b, v140
	v_rcp_f32_e32 v150, v150
	v_rcp_f32_e32 v151, v151
	v_exp_f32_e32 v140, v140
	v_mul_f32_e32 v149, 0xbfb8aa3b, v149
	v_exp_f32_e32 v149, v149
	v_pk_add_f32 v[154:155], v[154:155], 1.0 op_sel_hi:[1,0]
	v_add_f32_e32 v140, 1.0, v140
	v_pk_mul_f32 v[150:151], v[154:155], v[150:151]
	v_lshlrev_b32_e32 v148, 16, v144
	v_pk_mul_f32 v[86:87], v[86:87], v[150:151]
	v_and_b32_e32 v144, 0xffff0000, v144
	v_rcp_f32_e32 v151, v140
	v_lshlrev_b32_e32 v140, 16, v145
	v_add_f32_e32 v149, 1.0, v149
	v_mul_f32_e32 v144, 0xbfb8aa3b, v144
	v_mul_f32_e32 v140, 0xbfb8aa3b, v140
	v_rcp_f32_e32 v150, v149
	v_exp_f32_e32 v149, v144
	v_exp_f32_e32 v144, v140
	v_lshlrev_b32_e32 v140, 16, v141
	v_and_b32_e32 v141, 0xffff0000, v141
	v_mul_f32_e32 v140, 0xbfb8aa3b, v140
	v_mul_f32_e32 v141, 0xbfb8aa3b, v141
	v_exp_f32_e32 v140, v140
	v_exp_f32_e32 v141, v141
	v_and_b32_e32 v145, 0xffff0000, v145
	v_mul_f32_e32 v145, 0xbfb8aa3b, v145
	v_add_f32_e32 v140, 1.0, v140
	v_exp_f32_e32 v145, v145
	v_add_f32_e32 v141, 1.0, v141
	v_rcp_f32_e32 v140, v140
	v_rcp_f32_e32 v141, v141
	v_pk_add_f32 v[144:145], v[144:145], 1.0 op_sel_hi:[1,0]
	v_pk_mul_f32 v[120:121], v[120:121], v[188:189]
	v_pk_add_f32 v[180:181], v[180:181], 1.0 op_sel_hi:[1,0]
	v_pk_mul_f32 v[140:141], v[144:145], v[140:141]
	v_pk_mul_f32 v[180:181], v[180:181], v[182:183]
	v_pk_mul_f32 v[82:83], v[82:83], v[140:141]
	v_lshlrev_b32_e32 v141, 16, v142
	v_mul_f32_e32 v141, 0xbfb8aa3b, v141
	v_and_b32_e32 v142, 0xffff0000, v142
	v_exp_f32_e32 v141, v141
	v_mul_f32_e32 v142, 0xbfb8aa3b, v142
	v_exp_f32_e32 v142, v142
	v_lshlrev_b32_e32 v140, 16, v146
	v_add_f32_e32 v141, 1.0, v141
	v_rcp_f32_e32 v144, v141
	v_and_b32_e32 v141, 0xffff0000, v146
	v_add_f32_e32 v142, 1.0, v142
	v_mul_f32_e32 v140, 0xbfb8aa3b, v140
	v_mul_f32_e32 v141, 0xbfb8aa3b, v141
	v_rcp_f32_e32 v145, v142
	v_lshlrev_b32_e32 v142, 16, v147
	v_exp_f32_e32 v140, v140
	v_exp_f32_e32 v141, v141
	v_mul_f32_e32 v142, 0xbfb8aa3b, v142
	v_exp_f32_e32 v146, v142
	v_lshlrev_b32_e32 v142, 16, v143
	v_and_b32_e32 v143, 0xffff0000, v143
	v_mul_f32_e32 v142, 0xbfb8aa3b, v142
	v_mul_f32_e32 v143, 0xbfb8aa3b, v143
	v_exp_f32_e32 v142, v142
	v_exp_f32_e32 v143, v143
	v_pk_add_f32 v[140:141], v[140:141], 1.0 op_sel_hi:[1,0]
	v_and_b32_e32 v147, 0xffff0000, v147
	v_pk_mul_f32 v[140:141], v[140:141], v[144:145]
	v_mul_f32_e32 v147, 0xbfb8aa3b, v147
	v_pk_mul_f32 v[76:77], v[76:77], v[140:141]
	v_lshlrev_b32_e32 v141, 16, v132
	v_and_b32_e32 v132, 0xffff0000, v132
	v_add_f32_e32 v142, 1.0, v142
	v_exp_f32_e32 v147, v147
	v_add_f32_e32 v143, 1.0, v143
	v_mul_f32_e32 v132, 0xbfb8aa3b, v132
	v_rcp_f32_e32 v142, v142
	v_rcp_f32_e32 v143, v143
	v_exp_f32_e32 v132, v132
	v_mul_f32_e32 v141, 0xbfb8aa3b, v141
	v_exp_f32_e32 v141, v141
	v_pk_add_f32 v[146:147], v[146:147], 1.0 op_sel_hi:[1,0]
	v_add_f32_e32 v132, 1.0, v132
	v_pk_mul_f32 v[142:143], v[146:147], v[142:143]
	v_lshlrev_b32_e32 v140, 16, v136
	v_pk_mul_f32 v[78:79], v[78:79], v[142:143]
	v_and_b32_e32 v136, 0xffff0000, v136
	v_rcp_f32_e32 v143, v132
	v_lshlrev_b32_e32 v132, 16, v137
	v_add_f32_e32 v141, 1.0, v141
	v_mul_f32_e32 v136, 0xbfb8aa3b, v136
	v_mul_f32_e32 v132, 0xbfb8aa3b, v132
	v_rcp_f32_e32 v142, v141
	v_exp_f32_e32 v141, v136
	v_exp_f32_e32 v136, v132
	v_lshlrev_b32_e32 v132, 16, v133
	v_and_b32_e32 v133, 0xffff0000, v133
	v_mul_f32_e32 v132, 0xbfb8aa3b, v132
	v_mul_f32_e32 v133, 0xbfb8aa3b, v133
	v_exp_f32_e32 v132, v132
	v_exp_f32_e32 v133, v133
	v_and_b32_e32 v137, 0xffff0000, v137
	v_mul_f32_e32 v137, 0xbfb8aa3b, v137
	v_add_f32_e32 v132, 1.0, v132
	v_exp_f32_e32 v137, v137
	v_add_f32_e32 v133, 1.0, v133
	v_rcp_f32_e32 v132, v132
	v_rcp_f32_e32 v133, v133
	v_pk_add_f32 v[136:137], v[136:137], 1.0 op_sel_hi:[1,0]
	v_pk_mul_f32 v[112:113], v[112:113], v[180:181]
	v_mul_f32_e32 v172, 0xbfb8aa3b, v172
	v_pk_mul_f32 v[132:133], v[136:137], v[132:133]
	v_mul_f32_e32 v164, 0xbfb8aa3b, v164
	v_pk_mul_f32 v[74:75], v[74:75], v[132:133]
	v_lshlrev_b32_e32 v133, 16, v134
	v_mul_f32_e32 v133, 0xbfb8aa3b, v133
	v_exp_f32_e32 v133, v133
	v_and_b32_e32 v134, 0xffff0000, v134
	v_mul_f32_e32 v134, 0xbfb8aa3b, v134
	v_exp_f32_e32 v134, v134
	v_add_f32_e32 v133, 1.0, v133
	v_lshlrev_b32_e32 v132, 16, v138
	v_rcp_f32_e32 v136, v133
	v_and_b32_e32 v133, 0xffff0000, v138
	v_mul_f32_e32 v132, 0xbfb8aa3b, v132
	v_mul_f32_e32 v133, 0xbfb8aa3b, v133
	v_exp_f32_e32 v132, v132
	v_exp_f32_e32 v133, v133
	v_add_f32_e32 v134, 1.0, v134
	v_rcp_f32_e32 v137, v134
	v_lshlrev_b32_e32 v134, 16, v139
	v_mul_f32_e32 v134, 0xbfb8aa3b, v134
	v_exp_f32_e32 v138, v134
	v_lshlrev_b32_e32 v134, 16, v135
	v_and_b32_e32 v135, 0xffff0000, v135
	v_mul_f32_e32 v134, 0xbfb8aa3b, v134
	v_mul_f32_e32 v135, 0xbfb8aa3b, v135
	v_pk_add_f32 v[132:133], v[132:133], 1.0 op_sel_hi:[1,0]
	v_exp_f32_e32 v134, v134
	v_exp_f32_e32 v135, v135
	v_pk_mul_f32 v[132:133], v[132:133], v[136:137]
	v_and_b32_e32 v139, 0xffff0000, v139
	v_pk_mul_f32 v[68:69], v[68:69], v[132:133]
	v_add_u32_e32 v132, 0x80, v2
	v_mad_i64_i32 v[132:133], s[24:25], v132, s61, v[0:1]
	v_mul_f32_e32 v139, 0xbfb8aa3b, v139
	global_load_dwordx4 v[188:191], v[132:133], off
	v_add_f32_e32 v134, 1.0, v134
	v_exp_f32_e32 v139, v139
	v_add_f32_e32 v135, 1.0, v135
	v_rcp_f32_e32 v134, v134
	v_rcp_f32_e32 v135, v135
	v_pk_add_f32 v[138:139], v[138:139], 1.0 op_sel_hi:[1,0]
	v_exp_f32_e32 v172, v172
	v_exp_f32_e32 v164, v164
	v_pk_mul_f32 v[134:135], v[138:139], v[134:135]
	v_mul_f32_e32 v156, 0xbfb8aa3b, v156
; __device__ __forceinline__ float lo16(unsigned w) { return __uint_as_float(w << 16); }
; __device__ __forceinline__ float hi16(unsigned w) { return __uint_as_float(w & 0xffff0000u); }
;     __device__ __forceinline__ void mid(AccT& acc, const pg8::Unit& u, int which, int wr, int wc, int fr, int fq) const {
;     ...
;             for (int m = 0; m < 4; ++m)
; #pragma unroll
;                 for (int bj = 0; bj < 2; ++bj) { const bf16_t* zr = zG + (size_t)(row0 + ai * 128 + m * 16) * NZG + cb + bj * 128; gn[m][bj] = *(const u32x4*)(zr + onum); gd[m][bj] = *(const u32x4*)(zr + oden); }
; #pragma unroll
;             for (int m = 0; m < 4; ++m)
; #pragma unroll
;                 for (int bj = 0; bj < 2; ++bj)
; #pragma unroll
;                     for (int q = 0; q < 4; ++q) {
;                         const float r0 = (1.0f + __expf(-lo16(gd[m][bj][q]))) * __builtin_amdgcn_rcpf(1.0f + __expf(-lo16(gn[m][bj][q]))), r1 = (1.0f + __expf(-hi16(gd[m][bj][q]))) * __builtin_amdgcn_rcpf(1.0f + __expf(-hi16(gn[m][bj][q])));
;                         acc[ai][bj][m][q >> 1][(q & 1) * 2] *= r0; acc[ai][bj][m][q >> 1][(q & 1) * 2 + 1] *= r1;
;                     }
	v_pk_mul_f32 v[70:71], v[70:71], v[134:135]
	v_add_co_u32_e32 v134, vcc, s94, v132
	v_pk_add_f32 v[172:173], v[172:173], 1.0 op_sel_hi:[1,0]
	s_nop 0
	v_addc_co_u32_e32 v135, vcc, 0, v133, vcc
	global_load_dwordx4 v[192:195], v[134:135], off
	global_load_dwordx4 v[180:183], v[132:133], off offset:256
	global_load_dwordx4 v[184:187], v[134:135], off offset:256
	v_add_u32_e32 v132, 0x90, v2
	v_mad_i64_i32 v[132:133], s[24:25], v132, s61, v[0:1]
	v_pk_add_f32 v[164:165], v[164:165], 1.0 op_sel_hi:[1,0]
	v_add_co_u32_e32 v134, vcc, s94, v132
	v_pk_mul_f32 v[172:173], v[172:173], v[174:175]
	v_pk_mul_f32 v[164:165], v[164:165], v[166:167]
	v_mul_f32_e32 v148, 0xbfb8aa3b, v148
	v_mul_f32_e32 v140, 0xbfb8aa3b, v140
	v_addc_co_u32_e32 v135, vcc, 0, v133, vcc
	v_mul_f32_e32 v211, 0xbfb8aa3b, v211
	v_pk_mul_f32 v[104:105], v[104:105], v[172:173]
	v_pk_mul_f32 v[96:97], v[96:97], v[164:165]
	v_exp_f32_e32 v156, v156
	v_exp_f32_e32 v148, v148
	v_exp_f32_e32 v140, v140
	global_load_dwordx4 v[172:175], v[132:133], off
	global_load_dwordx4 v[176:179], v[134:135], off
	global_load_dwordx4 v[164:167], v[132:133], off offset:256
	global_load_dwordx4 v[168:171], v[134:135], off offset:256
	v_add_u32_e32 v132, 0xa0, v2
	v_exp_f32_e32 v211, v211
	v_mad_i64_i32 v[132:133], s[24:25], v132, s61, v[0:1]
	v_add_co_u32_e32 v134, vcc, s94, v132
	v_add_u32_e32 v2, 0xb0, v2
	s_nop 0
	v_addc_co_u32_e32 v135, vcc, 0, v133, vcc
	v_mad_i64_i32 v[0:1], s[24:25], v2, s61, v[0:1]
	v_pk_add_f32 v[156:157], v[156:157], 1.0 op_sel_hi:[1,0]
	v_pk_add_f32 v[148:149], v[148:149], 1.0 op_sel_hi:[1,0]
	v_pk_add_f32 v[140:141], v[140:141], 1.0 op_sel_hi:[1,0]
	v_add_co_u32_e32 v136, vcc, s94, v0
	v_add_f32_e32 v211, 1.0, v211
	v_pk_mul_f32 v[156:157], v[156:157], v[158:159]
	v_pk_mul_f32 v[148:149], v[148:149], v[150:151]
	v_pk_mul_f32 v[140:141], v[140:141], v[142:143]
	v_addc_co_u32_e32 v137, vcc, 0, v1, vcc
	v_rcp_f32_e32 v232, v211
	v_pk_mul_f32 v[88:89], v[88:89], v[156:157]
	v_pk_mul_f32 v[80:81], v[80:81], v[148:149]
	v_pk_mul_f32 v[72:73], v[72:73], v[140:141]
	global_load_dwordx4 v[156:159], v[132:133], off
	global_load_dwordx4 v[160:163], v[134:135], off
	global_load_dwordx4 v[148:151], v[132:133], off offset:256
	global_load_dwordx4 v[152:155], v[134:135], off offset:256
	global_load_dwordx4 v[140:143], v[0:1], off
	global_load_dwordx4 v[144:147], v[136:137], off
	s_nop 0
	global_load_dwordx4 v[132:135], v[0:1], off offset:256
	s_nop 0
	global_load_dwordx4 v[136:139], v[136:137], off offset:256
	v_pk_add_f32 v[230:231], v[230:231], 1.0 op_sel_hi:[1,0]
	s_waitcnt vmcnt(0)
	v_and_b32_e32 v2, 0xffff0000, v188
	v_mul_f32_e32 v2, 0xbfb8aa3b, v2
	v_lshlrev_b32_e32 v1, 16, v188
	v_exp_f32_e32 v2, v2
	v_mul_f32_e32 v1, 0xbfb8aa3b, v1
	v_exp_f32_e32 v1, v1
	v_pk_mul_f32 v[230:231], v[230:231], v[232:233]
	v_add_f32_e32 v2, 1.0, v2
	v_pk_mul_f32 v[128:129], v[128:129], v[230:231]
	v_rcp_f32_e32 v231, v2
	v_add_f32_e32 v1, 1.0, v1
	v_rcp_f32_e32 v230, v1
	v_lshlrev_b32_e32 v2, 16, v193
	v_mul_f32_e32 v2, 0xbfb8aa3b, v2
	v_lshlrev_b32_e32 v0, 16, v192
	v_and_b32_e32 v1, 0xffff0000, v192
	v_exp_f32_e32 v192, v2
	v_lshlrev_b32_e32 v2, 16, v189
	v_mul_f32_e32 v2, 0xbfb8aa3b, v2
	v_exp_f32_e32 v2, v2
	v_mul_f32_e32 v0, 0xbfb8aa3b, v0
	v_mul_f32_e32 v1, 0xbfb8aa3b, v1
	v_exp_f32_e32 v0, v0
	v_add_f32_e32 v2, 1.0, v2
	v_rcp_f32_e32 v188, v2
	v_and_b32_e32 v2, 0xffff0000, v193
	v_mul_f32_e32 v2, 0xbfb8aa3b, v2
	v_exp_f32_e32 v193, v2
	v_and_b32_e32 v2, 0xffff0000, v189
	v_mul_f32_e32 v2, 0xbfb8aa3b, v2
	v_exp_f32_e32 v2, v2
	v_pk_add_f32 v[192:193], v[192:193], 1.0 op_sel_hi:[1,0]
	v_exp_f32_e32 v1, v1
	v_add_f32_e32 v2, 1.0, v2
	v_rcp_f32_e32 v189, v2
	v_and_b32_e32 v2, 0xffff0000, v190
	v_mul_f32_e32 v2, 0xbfb8aa3b, v2
	v_exp_f32_e32 v2, v2
	v_pk_mul_f32 v[188:189], v[192:193], v[188:189]
	v_pk_add_f32 v[0:1], v[0:1], 1.0 op_sel_hi:[1,0]
	v_pk_mul_f32 v[66:67], v[66:67], v[188:189]
	v_add_f32_e32 v2, 1.0, v2
	v_rcp_f32_e32 v189, v2
	v_lshlrev_b32_e32 v2, 16, v195
	v_mul_f32_e32 v2, 0xbfb8aa3b, v2
	v_exp_f32_e32 v192, v2
	v_lshlrev_b32_e32 v2, 16, v191
	v_mul_f32_e32 v2, 0xbfb8aa3b, v2
	v_pk_mul_f32 v[0:1], v[0:1], v[230:231]
	v_exp_f32_e32 v2, v2
	v_pk_mul_f32 v[64:65], v[64:65], v[0:1]
	v_lshlrev_b32_e32 v1, 16, v190
	v_mul_f32_e32 v1, 0xbfb8aa3b, v1
	v_exp_f32_e32 v1, v1
	v_add_f32_e32 v2, 1.0, v2
	v_rcp_f32_e32 v190, v2
	v_and_b32_e32 v2, 0xffff0000, v195
	v_mul_f32_e32 v2, 0xbfb8aa3b, v2
	v_add_f32_e32 v1, 1.0, v1
	v_exp_f32_e32 v193, v2
	v_and_b32_e32 v2, 0xffff0000, v191
	v_lshlrev_b32_e32 v0, 16, v194
	v_rcp_f32_e32 v188, v1
	v_and_b32_e32 v1, 0xffff0000, v194
	v_mul_f32_e32 v2, 0xbfb8aa3b, v2
	v_mul_f32_e32 v0, 0xbfb8aa3b, v0
	v_mul_f32_e32 v1, 0xbfb8aa3b, v1
	v_exp_f32_e32 v2, v2
	v_exp_f32_e32 v0, v0
	v_exp_f32_e32 v1, v1
	v_pk_add_f32 v[192:193], v[192:193], 1.0 op_sel_hi:[1,0]
	v_add_f32_e32 v2, 1.0, v2
	v_rcp_f32_e32 v191, v2
	v_pk_add_f32 v[0:1], v[0:1], 1.0 op_sel_hi:[1,0]
	v_and_b32_e32 v2, 0xffff0000, v180
	v_pk_mul_f32 v[0:1], v[0:1], v[188:189]
	v_mul_f32_e32 v2, 0xbfb8aa3b, v2
	v_pk_mul_f32 v[60:61], v[60:61], v[0:1]
	v_lshlrev_b32_e32 v1, 16, v180
	v_exp_f32_e32 v2, v2
	v_mul_f32_e32 v1, 0xbfb8aa3b, v1
	v_exp_f32_e32 v1, v1
	v_pk_mul_f32 v[188:189], v[192:193], v[190:191]
	v_add_f32_e32 v2, 1.0, v2
	v_pk_mul_f32 v[62:63], v[62:63], v[188:189]
	v_rcp_f32_e32 v189, v2
	v_lshlrev_b32_e32 v2, 16, v185
	v_add_f32_e32 v1, 1.0, v1
	v_mul_f32_e32 v2, 0xbfb8aa3b, v2
	v_lshlrev_b32_e32 v0, 16, v184
	v_rcp_f32_e32 v188, v1
	v_and_b32_e32 v1, 0xffff0000, v184
	v_exp_f32_e32 v184, v2
	v_lshlrev_b32_e32 v2, 16, v181
	v_mul_f32_e32 v2, 0xbfb8aa3b, v2
	v_exp_f32_e32 v2, v2
; __device__ __forceinline__ float lo16(unsigned w) { return __uint_as_float(w << 16); }
; __device__ __forceinline__ float hi16(unsigned w) { return __uint_as_float(w & 0xffff0000u); }
;     __device__ __forceinline__ void mid(AccT& acc, const pg8::Unit& u, int which, int wr, int wc, int fr, int fq) const {
;     ...
;             for (int m = 0; m < 4; ++m)
; #pragma unroll
;                 for (int bj = 0; bj < 2; ++bj) { const bf16_t* zr = zG + (size_t)(row0 + ai * 128 + m * 16) * NZG + cb + bj * 128; gn[m][bj] = *(const u32x4*)(zr + onum); gd[m][bj] = *(const u32x4*)(zr + oden); }
; #pragma unroll
;             for (int m = 0; m < 4; ++m)
; #pragma unroll
;                 for (int bj = 0; bj < 2; ++bj)
; #pragma unroll
;                     for (int q = 0; q < 4; ++q) {
;                         const float r0 = (1.0f + __expf(-lo16(gd[m][bj][q]))) * __builtin_amdgcn_rcpf(1.0f + __expf(-lo16(gn[m][bj][q]))), r1 = (1.0f + __expf(-hi16(gd[m][bj][q]))) * __builtin_amdgcn_rcpf(1.0f + __expf(-hi16(gn[m][bj][q])));
;                         acc[ai][bj][m][q >> 1][(q & 1) * 2] *= r0; acc[ai][bj][m][q >> 1][(q & 1) * 2 + 1] *= r1;
;                     }
	v_mul_f32_e32 v0, 0xbfb8aa3b, v0
	v_mul_f32_e32 v1, 0xbfb8aa3b, v1
	v_exp_f32_e32 v0, v0
	v_add_f32_e32 v2, 1.0, v2
	v_rcp_f32_e32 v180, v2
	v_and_b32_e32 v2, 0xffff0000, v185
	v_mul_f32_e32 v2, 0xbfb8aa3b, v2
	v_exp_f32_e32 v185, v2
	v_and_b32_e32 v2, 0xffff0000, v181
	v_mul_f32_e32 v2, 0xbfb8aa3b, v2
	v_exp_f32_e32 v2, v2
	v_pk_add_f32 v[184:185], v[184:185], 1.0 op_sel_hi:[1,0]
	v_exp_f32_e32 v1, v1
	v_add_f32_e32 v2, 1.0, v2
	v_rcp_f32_e32 v181, v2
	v_and_b32_e32 v2, 0xffff0000, v182
	v_mul_f32_e32 v2, 0xbfb8aa3b, v2
	v_exp_f32_e32 v2, v2
	v_pk_mul_f32 v[180:181], v[184:185], v[180:181]
	v_pk_add_f32 v[0:1], v[0:1], 1.0 op_sel_hi:[1,0]
	v_pk_mul_f32 v[58:59], v[58:59], v[180:181]
	v_add_f32_e32 v2, 1.0, v2
	v_rcp_f32_e32 v181, v2
	v_lshlrev_b32_e32 v2, 16, v187
	v_mul_f32_e32 v2, 0xbfb8aa3b, v2
	v_exp_f32_e32 v184, v2
	v_lshlrev_b32_e32 v2, 16, v183
	v_mul_f32_e32 v2, 0xbfb8aa3b, v2
	v_pk_mul_f32 v[0:1], v[0:1], v[188:189]
	v_exp_f32_e32 v2, v2
	v_pk_mul_f32 v[56:57], v[56:57], v[0:1]
	v_lshlrev_b32_e32 v1, 16, v182
	v_mul_f32_e32 v1, 0xbfb8aa3b, v1
	v_exp_f32_e32 v1, v1
	v_add_f32_e32 v2, 1.0, v2
	v_rcp_f32_e32 v182, v2
	v_and_b32_e32 v2, 0xffff0000, v187
	v_mul_f32_e32 v2, 0xbfb8aa3b, v2
	v_add_f32_e32 v1, 1.0, v1
	v_exp_f32_e32 v185, v2
	v_and_b32_e32 v2, 0xffff0000, v183
	v_lshlrev_b32_e32 v0, 16, v186
	v_rcp_f32_e32 v180, v1
	v_and_b32_e32 v1, 0xffff0000, v186
	v_mul_f32_e32 v2, 0xbfb8aa3b, v2
	v_mul_f32_e32 v0, 0xbfb8aa3b, v0
	v_mul_f32_e32 v1, 0xbfb8aa3b, v1
	v_exp_f32_e32 v2, v2
	v_exp_f32_e32 v0, v0
	v_exp_f32_e32 v1, v1
	v_pk_add_f32 v[184:185], v[184:185], 1.0 op_sel_hi:[1,0]
	v_add_f32_e32 v2, 1.0, v2
	v_rcp_f32_e32 v183, v2
	v_pk_add_f32 v[0:1], v[0:1], 1.0 op_sel_hi:[1,0]
	v_and_b32_e32 v2, 0xffff0000, v172
	v_pk_mul_f32 v[0:1], v[0:1], v[180:181]
	v_mul_f32_e32 v2, 0xbfb8aa3b, v2
	v_pk_mul_f32 v[52:53], v[52:53], v[0:1]
	v_lshlrev_b32_e32 v1, 16, v172
	v_exp_f32_e32 v2, v2
	v_mul_f32_e32 v1, 0xbfb8aa3b, v1
	v_exp_f32_e32 v1, v1
	v_pk_mul_f32 v[180:181], v[184:185], v[182:183]
	v_add_f32_e32 v2, 1.0, v2
	v_pk_mul_f32 v[54:55], v[54:55], v[180:181]
	v_rcp_f32_e32 v181, v2
	v_lshlrev_b32_e32 v2, 16, v177
	v_add_f32_e32 v1, 1.0, v1
	v_mul_f32_e32 v2, 0xbfb8aa3b, v2
	v_lshlrev_b32_e32 v0, 16, v176
	v_rcp_f32_e32 v180, v1
	v_and_b32_e32 v1, 0xffff0000, v176
	v_exp_f32_e32 v176, v2
	v_lshlrev_b32_e32 v2, 16, v173
	v_mul_f32_e32 v2, 0xbfb8aa3b, v2
	v_exp_f32_e32 v2, v2
	v_mul_f32_e32 v0, 0xbfb8aa3b, v0
	v_mul_f32_e32 v1, 0xbfb8aa3b, v1
	v_exp_f32_e32 v0, v0
	v_add_f32_e32 v2, 1.0, v2
	v_rcp_f32_e32 v172, v2
	v_and_b32_e32 v2, 0xffff0000, v177
	v_mul_f32_e32 v2, 0xbfb8aa3b, v2
	v_exp_f32_e32 v177, v2
	v_and_b32_e32 v2, 0xffff0000, v173
	v_mul_f32_e32 v2, 0xbfb8aa3b, v2
	v_exp_f32_e32 v2, v2
	v_pk_add_f32 v[176:177], v[176:177], 1.0 op_sel_hi:[1,0]
	v_exp_f32_e32 v1, v1
	v_add_f32_e32 v2, 1.0, v2
	v_rcp_f32_e32 v173, v2
	v_and_b32_e32 v2, 0xffff0000, v174
	v_mul_f32_e32 v2, 0xbfb8aa3b, v2
	v_exp_f32_e32 v2, v2
	v_pk_mul_f32 v[172:173], v[176:177], v[172:173]
	v_pk_add_f32 v[0:1], v[0:1], 1.0 op_sel_hi:[1,0]
	v_pk_mul_f32 v[50:51], v[50:51], v[172:173]
	v_add_f32_e32 v2, 1.0, v2
	v_rcp_f32_e32 v173, v2
	v_lshlrev_b32_e32 v2, 16, v179
	v_mul_f32_e32 v2, 0xbfb8aa3b, v2
	v_exp_f32_e32 v176, v2
	v_lshlrev_b32_e32 v2, 16, v175
	v_mul_f32_e32 v2, 0xbfb8aa3b, v2
	v_pk_mul_f32 v[0:1], v[0:1], v[180:181]
	v_exp_f32_e32 v2, v2
	v_pk_mul_f32 v[48:49], v[48:49], v[0:1]
	v_lshlrev_b32_e32 v1, 16, v174
	v_mul_f32_e32 v1, 0xbfb8aa3b, v1
	v_exp_f32_e32 v1, v1
	v_add_f32_e32 v2, 1.0, v2
	v_rcp_f32_e32 v174, v2
	v_and_b32_e32 v2, 0xffff0000, v179
	v_mul_f32_e32 v2, 0xbfb8aa3b, v2
	v_add_f32_e32 v1, 1.0, v1
	v_exp_f32_e32 v177, v2
	v_and_b32_e32 v2, 0xffff0000, v175
	v_lshlrev_b32_e32 v0, 16, v178
	v_rcp_f32_e32 v172, v1
	v_and_b32_e32 v1, 0xffff0000, v178
	v_mul_f32_e32 v2, 0xbfb8aa3b, v2
	v_mul_f32_e32 v0, 0xbfb8aa3b, v0
	v_mul_f32_e32 v1, 0xbfb8aa3b, v1
	v_exp_f32_e32 v2, v2
	v_exp_f32_e32 v0, v0
	v_exp_f32_e32 v1, v1
	v_pk_add_f32 v[176:177], v[176:177], 1.0 op_sel_hi:[1,0]
	v_add_f32_e32 v2, 1.0, v2
	v_rcp_f32_e32 v175, v2
	v_pk_add_f32 v[0:1], v[0:1], 1.0 op_sel_hi:[1,0]
	v_and_b32_e32 v2, 0xffff0000, v164
	v_pk_mul_f32 v[0:1], v[0:1], v[172:173]
	v_mul_f32_e32 v2, 0xbfb8aa3b, v2
	v_pk_mul_f32 v[44:45], v[44:45], v[0:1]
	v_lshlrev_b32_e32 v1, 16, v164
	v_exp_f32_e32 v2, v2
	v_mul_f32_e32 v1, 0xbfb8aa3b, v1
	v_exp_f32_e32 v1, v1
	v_pk_mul_f32 v[172:173], v[176:177], v[174:175]
	v_add_f32_e32 v2, 1.0, v2
	v_pk_mul_f32 v[46:47], v[46:47], v[172:173]
	v_rcp_f32_e32 v173, v2
	v_lshlrev_b32_e32 v2, 16, v169
	v_add_f32_e32 v1, 1.0, v1
	v_mul_f32_e32 v2, 0xbfb8aa3b, v2
	v_lshlrev_b32_e32 v0, 16, v168
	v_rcp_f32_e32 v172, v1
	v_and_b32_e32 v1, 0xffff0000, v168
	v_exp_f32_e32 v168, v2
	v_lshlrev_b32_e32 v2, 16, v165
	v_mul_f32_e32 v2, 0xbfb8aa3b, v2
	v_exp_f32_e32 v2, v2
	v_mul_f32_e32 v0, 0xbfb8aa3b, v0
	v_mul_f32_e32 v1, 0xbfb8aa3b, v1
	v_exp_f32_e32 v0, v0
	v_add_f32_e32 v2, 1.0, v2
	v_rcp_f32_e32 v164, v2
	v_and_b32_e32 v2, 0xffff0000, v169
	v_mul_f32_e32 v2, 0xbfb8aa3b, v2
	v_exp_f32_e32 v169, v2
	v_and_b32_e32 v2, 0xffff0000, v165
	v_mul_f32_e32 v2, 0xbfb8aa3b, v2
	v_exp_f32_e32 v2, v2
	v_pk_add_f32 v[168:169], v[168:169], 1.0 op_sel_hi:[1,0]
	v_exp_f32_e32 v1, v1
	v_add_f32_e32 v2, 1.0, v2
	v_rcp_f32_e32 v165, v2
	v_and_b32_e32 v2, 0xffff0000, v166
	v_mul_f32_e32 v2, 0xbfb8aa3b, v2
	v_exp_f32_e32 v2, v2
	v_pk_mul_f32 v[164:165], v[168:169], v[164:165]
	v_pk_add_f32 v[0:1], v[0:1], 1.0 op_sel_hi:[1,0]
	v_pk_mul_f32 v[42:43], v[42:43], v[164:165]
	v_add_f32_e32 v2, 1.0, v2
	v_rcp_f32_e32 v165, v2
	v_lshlrev_b32_e32 v2, 16, v171
; __device__ __forceinline__ float lo16(unsigned w) { return __uint_as_float(w << 16); }
; __device__ __forceinline__ float hi16(unsigned w) { return __uint_as_float(w & 0xffff0000u); }
;     __device__ __forceinline__ void mid(AccT& acc, const pg8::Unit& u, int which, int wr, int wc, int fr, int fq) const {
;     ...
;             for (int m = 0; m < 4; ++m)
; #pragma unroll
;                 for (int bj = 0; bj < 2; ++bj) { const bf16_t* zr = zG + (size_t)(row0 + ai * 128 + m * 16) * NZG + cb + bj * 128; gn[m][bj] = *(const u32x4*)(zr + onum); gd[m][bj] = *(const u32x4*)(zr + oden); }
; #pragma unroll
;             for (int m = 0; m < 4; ++m)
; #pragma unroll
;                 for (int bj = 0; bj < 2; ++bj)
; #pragma unroll
;                     for (int q = 0; q < 4; ++q) {
;                         const float r0 = (1.0f + __expf(-lo16(gd[m][bj][q]))) * __builtin_amdgcn_rcpf(1.0f + __expf(-lo16(gn[m][bj][q]))), r1 = (1.0f + __expf(-hi16(gd[m][bj][q]))) * __builtin_amdgcn_rcpf(1.0f + __expf(-hi16(gn[m][bj][q])));
;                         acc[ai][bj][m][q >> 1][(q & 1) * 2] *= r0; acc[ai][bj][m][q >> 1][(q & 1) * 2 + 1] *= r1;
;                     }
	v_mul_f32_e32 v2, 0xbfb8aa3b, v2
	v_exp_f32_e32 v168, v2
	v_lshlrev_b32_e32 v2, 16, v167
	v_mul_f32_e32 v2, 0xbfb8aa3b, v2
	v_pk_mul_f32 v[0:1], v[0:1], v[172:173]
	v_exp_f32_e32 v2, v2
	v_pk_mul_f32 v[40:41], v[40:41], v[0:1]
	v_lshlrev_b32_e32 v1, 16, v166
	v_mul_f32_e32 v1, 0xbfb8aa3b, v1
	v_exp_f32_e32 v1, v1
	v_add_f32_e32 v2, 1.0, v2
	v_rcp_f32_e32 v166, v2
	v_and_b32_e32 v2, 0xffff0000, v171
	v_mul_f32_e32 v2, 0xbfb8aa3b, v2
	v_add_f32_e32 v1, 1.0, v1
	v_exp_f32_e32 v169, v2
	v_and_b32_e32 v2, 0xffff0000, v167
	v_lshlrev_b32_e32 v0, 16, v170
	v_rcp_f32_e32 v164, v1
	v_and_b32_e32 v1, 0xffff0000, v170
	v_mul_f32_e32 v2, 0xbfb8aa3b, v2
	v_mul_f32_e32 v0, 0xbfb8aa3b, v0
	v_mul_f32_e32 v1, 0xbfb8aa3b, v1
	v_exp_f32_e32 v2, v2
	v_exp_f32_e32 v0, v0
	v_exp_f32_e32 v1, v1
	v_pk_add_f32 v[168:169], v[168:169], 1.0 op_sel_hi:[1,0]
	v_add_f32_e32 v2, 1.0, v2
	v_rcp_f32_e32 v167, v2
	v_pk_add_f32 v[0:1], v[0:1], 1.0 op_sel_hi:[1,0]
	v_and_b32_e32 v2, 0xffff0000, v156
	v_pk_mul_f32 v[0:1], v[0:1], v[164:165]
	v_mul_f32_e32 v2, 0xbfb8aa3b, v2
	v_pk_mul_f32 v[36:37], v[36:37], v[0:1]
	v_lshlrev_b32_e32 v1, 16, v156
	v_exp_f32_e32 v2, v2
	v_mul_f32_e32 v1, 0xbfb8aa3b, v1
	v_exp_f32_e32 v1, v1
	v_pk_mul_f32 v[164:165], v[168:169], v[166:167]
	v_add_f32_e32 v2, 1.0, v2
	v_pk_mul_f32 v[38:39], v[38:39], v[164:165]
	v_rcp_f32_e32 v165, v2
	v_lshlrev_b32_e32 v2, 16, v161
	v_add_f32_e32 v1, 1.0, v1
	v_mul_f32_e32 v2, 0xbfb8aa3b, v2
	v_lshlrev_b32_e32 v0, 16, v160
	v_rcp_f32_e32 v164, v1
	v_and_b32_e32 v1, 0xffff0000, v160
	v_exp_f32_e32 v160, v2
	v_lshlrev_b32_e32 v2, 16, v157
	v_mul_f32_e32 v2, 0xbfb8aa3b, v2
	v_exp_f32_e32 v2, v2
	v_mul_f32_e32 v0, 0xbfb8aa3b, v0
	v_mul_f32_e32 v1, 0xbfb8aa3b, v1
	v_exp_f32_e32 v0, v0
	v_add_f32_e32 v2, 1.0, v2
	v_rcp_f32_e32 v156, v2
	v_and_b32_e32 v2, 0xffff0000, v161
	v_mul_f32_e32 v2, 0xbfb8aa3b, v2
	v_exp_f32_e32 v161, v2
	v_and_b32_e32 v2, 0xffff0000, v157
	v_mul_f32_e32 v2, 0xbfb8aa3b, v2
	v_exp_f32_e32 v2, v2
	v_pk_add_f32 v[160:161], v[160:161], 1.0 op_sel_hi:[1,0]
	v_exp_f32_e32 v1, v1
	v_add_f32_e32 v2, 1.0, v2
	v_rcp_f32_e32 v157, v2
	v_and_b32_e32 v2, 0xffff0000, v158
	v_mul_f32_e32 v2, 0xbfb8aa3b, v2
	v_exp_f32_e32 v2, v2
	v_pk_mul_f32 v[156:157], v[160:161], v[156:157]
	v_pk_add_f32 v[0:1], v[0:1], 1.0 op_sel_hi:[1,0]
	v_pk_mul_f32 v[34:35], v[34:35], v[156:157]
	v_add_f32_e32 v2, 1.0, v2
	v_rcp_f32_e32 v157, v2
	v_lshlrev_b32_e32 v2, 16, v163
	v_mul_f32_e32 v2, 0xbfb8aa3b, v2
	v_exp_f32_e32 v160, v2
	v_lshlrev_b32_e32 v2, 16, v159
	v_mul_f32_e32 v2, 0xbfb8aa3b, v2
	v_pk_mul_f32 v[0:1], v[0:1], v[164:165]
	v_exp_f32_e32 v2, v2
	v_pk_mul_f32 v[32:33], v[32:33], v[0:1]
	v_lshlrev_b32_e32 v1, 16, v158
	v_mul_f32_e32 v1, 0xbfb8aa3b, v1
	v_exp_f32_e32 v1, v1
	v_add_f32_e32 v2, 1.0, v2
	v_rcp_f32_e32 v158, v2
	v_and_b32_e32 v2, 0xffff0000, v163
	v_mul_f32_e32 v2, 0xbfb8aa3b, v2
	v_add_f32_e32 v1, 1.0, v1
	v_exp_f32_e32 v161, v2
	v_and_b32_e32 v2, 0xffff0000, v159
	v_lshlrev_b32_e32 v0, 16, v162
	v_rcp_f32_e32 v156, v1
	v_and_b32_e32 v1, 0xffff0000, v162
	v_mul_f32_e32 v2, 0xbfb8aa3b, v2
	v_mul_f32_e32 v0, 0xbfb8aa3b, v0
	v_mul_f32_e32 v1, 0xbfb8aa3b, v1
	v_exp_f32_e32 v2, v2
	v_exp_f32_e32 v0, v0
	v_exp_f32_e32 v1, v1
	v_pk_add_f32 v[160:161], v[160:161], 1.0 op_sel_hi:[1,0]
	v_add_f32_e32 v2, 1.0, v2
	v_rcp_f32_e32 v159, v2
	v_pk_add_f32 v[0:1], v[0:1], 1.0 op_sel_hi:[1,0]
	v_and_b32_e32 v2, 0xffff0000, v148
	v_pk_mul_f32 v[0:1], v[0:1], v[156:157]
	v_mul_f32_e32 v2, 0xbfb8aa3b, v2
	v_pk_mul_f32 v[28:29], v[28:29], v[0:1]
	v_lshlrev_b32_e32 v1, 16, v148
	v_exp_f32_e32 v2, v2
	v_mul_f32_e32 v1, 0xbfb8aa3b, v1
	v_exp_f32_e32 v1, v1
	v_pk_mul_f32 v[156:157], v[160:161], v[158:159]
	v_add_f32_e32 v2, 1.0, v2
	v_pk_mul_f32 v[30:31], v[30:31], v[156:157]
	v_rcp_f32_e32 v157, v2
	v_lshlrev_b32_e32 v2, 16, v153
	v_add_f32_e32 v1, 1.0, v1
	v_mul_f32_e32 v2, 0xbfb8aa3b, v2
	v_lshlrev_b32_e32 v0, 16, v152
	v_rcp_f32_e32 v156, v1
	v_and_b32_e32 v1, 0xffff0000, v152
	v_exp_f32_e32 v152, v2
	v_lshlrev_b32_e32 v2, 16, v149
	v_mul_f32_e32 v2, 0xbfb8aa3b, v2
	v_exp_f32_e32 v2, v2
	v_mul_f32_e32 v0, 0xbfb8aa3b, v0
	v_mul_f32_e32 v1, 0xbfb8aa3b, v1
	v_exp_f32_e32 v0, v0
	v_add_f32_e32 v2, 1.0, v2
	v_rcp_f32_e32 v148, v2
	v_and_b32_e32 v2, 0xffff0000, v153
	v_mul_f32_e32 v2, 0xbfb8aa3b, v2
	v_exp_f32_e32 v153, v2
	v_and_b32_e32 v2, 0xffff0000, v149
	v_mul_f32_e32 v2, 0xbfb8aa3b, v2
	v_exp_f32_e32 v2, v2
	v_pk_add_f32 v[152:153], v[152:153], 1.0 op_sel_hi:[1,0]
	v_exp_f32_e32 v1, v1
	v_add_f32_e32 v2, 1.0, v2
	v_rcp_f32_e32 v149, v2
	v_and_b32_e32 v2, 0xffff0000, v150
	v_mul_f32_e32 v2, 0xbfb8aa3b, v2
	v_exp_f32_e32 v2, v2
	v_pk_mul_f32 v[148:149], v[152:153], v[148:149]
	v_pk_add_f32 v[0:1], v[0:1], 1.0 op_sel_hi:[1,0]
	v_pk_mul_f32 v[26:27], v[26:27], v[148:149]
	v_add_f32_e32 v2, 1.0, v2
	v_rcp_f32_e32 v149, v2
	v_lshlrev_b32_e32 v2, 16, v155
	v_mul_f32_e32 v2, 0xbfb8aa3b, v2
	v_exp_f32_e32 v152, v2
	v_lshlrev_b32_e32 v2, 16, v151
	v_mul_f32_e32 v2, 0xbfb8aa3b, v2
	v_pk_mul_f32 v[0:1], v[0:1], v[156:157]
	v_exp_f32_e32 v2, v2
	v_pk_mul_f32 v[24:25], v[24:25], v[0:1]
	v_lshlrev_b32_e32 v1, 16, v150
	v_mul_f32_e32 v1, 0xbfb8aa3b, v1
	v_exp_f32_e32 v1, v1
	v_add_f32_e32 v2, 1.0, v2
	v_rcp_f32_e32 v150, v2
	v_and_b32_e32 v2, 0xffff0000, v155
	v_mul_f32_e32 v2, 0xbfb8aa3b, v2
	v_add_f32_e32 v1, 1.0, v1
	v_exp_f32_e32 v153, v2
	v_and_b32_e32 v2, 0xffff0000, v151
	v_lshlrev_b32_e32 v0, 16, v154
	v_rcp_f32_e32 v148, v1
	v_and_b32_e32 v1, 0xffff0000, v154
	v_mul_f32_e32 v2, 0xbfb8aa3b, v2
	v_mul_f32_e32 v0, 0xbfb8aa3b, v0
	v_mul_f32_e32 v1, 0xbfb8aa3b, v1
	v_exp_f32_e32 v2, v2
	v_exp_f32_e32 v0, v0
	v_exp_f32_e32 v1, v1
; __device__ __forceinline__ float lo16(unsigned w) { return __uint_as_float(w << 16); }
; __device__ __forceinline__ float hi16(unsigned w) { return __uint_as_float(w & 0xffff0000u); }
;     __device__ __forceinline__ void mid(AccT& acc, const pg8::Unit& u, int which, int wr, int wc, int fr, int fq) const {
;     ...
;             for (int m = 0; m < 4; ++m)
; #pragma unroll
;                 for (int bj = 0; bj < 2; ++bj) { const bf16_t* zr = zG + (size_t)(row0 + ai * 128 + m * 16) * NZG + cb + bj * 128; gn[m][bj] = *(const u32x4*)(zr + onum); gd[m][bj] = *(const u32x4*)(zr + oden); }
; #pragma unroll
;             for (int m = 0; m < 4; ++m)
; #pragma unroll
;                 for (int bj = 0; bj < 2; ++bj)
; #pragma unroll
;                     for (int q = 0; q < 4; ++q) {
;                         const float r0 = (1.0f + __expf(-lo16(gd[m][bj][q]))) * __builtin_amdgcn_rcpf(1.0f + __expf(-lo16(gn[m][bj][q]))), r1 = (1.0f + __expf(-hi16(gd[m][bj][q]))) * __builtin_amdgcn_rcpf(1.0f + __expf(-hi16(gn[m][bj][q])));
;                         acc[ai][bj][m][q >> 1][(q & 1) * 2] *= r0; acc[ai][bj][m][q >> 1][(q & 1) * 2 + 1] *= r1;
;                     }
	v_pk_add_f32 v[152:153], v[152:153], 1.0 op_sel_hi:[1,0]
	v_add_f32_e32 v2, 1.0, v2
	v_rcp_f32_e32 v151, v2
	v_pk_add_f32 v[0:1], v[0:1], 1.0 op_sel_hi:[1,0]
	v_and_b32_e32 v2, 0xffff0000, v140
	v_pk_mul_f32 v[0:1], v[0:1], v[148:149]
	v_mul_f32_e32 v2, 0xbfb8aa3b, v2
	v_pk_mul_f32 v[20:21], v[20:21], v[0:1]
	v_lshlrev_b32_e32 v1, 16, v140
	v_exp_f32_e32 v2, v2
	v_mul_f32_e32 v1, 0xbfb8aa3b, v1
	v_exp_f32_e32 v1, v1
	v_pk_mul_f32 v[148:149], v[152:153], v[150:151]
	v_add_f32_e32 v2, 1.0, v2
	v_pk_mul_f32 v[22:23], v[22:23], v[148:149]
	v_rcp_f32_e32 v149, v2
	v_lshlrev_b32_e32 v2, 16, v145
	v_add_f32_e32 v1, 1.0, v1
	v_mul_f32_e32 v2, 0xbfb8aa3b, v2
	v_lshlrev_b32_e32 v0, 16, v144
	v_rcp_f32_e32 v148, v1
	v_and_b32_e32 v1, 0xffff0000, v144
	v_exp_f32_e32 v144, v2
	v_lshlrev_b32_e32 v2, 16, v141
	v_mul_f32_e32 v2, 0xbfb8aa3b, v2
	v_exp_f32_e32 v2, v2
	v_mul_f32_e32 v0, 0xbfb8aa3b, v0
	v_mul_f32_e32 v1, 0xbfb8aa3b, v1
	v_exp_f32_e32 v0, v0
	v_add_f32_e32 v2, 1.0, v2
	v_rcp_f32_e32 v140, v2
	v_and_b32_e32 v2, 0xffff0000, v145
	v_mul_f32_e32 v2, 0xbfb8aa3b, v2
	v_exp_f32_e32 v145, v2
	v_and_b32_e32 v2, 0xffff0000, v141
	v_mul_f32_e32 v2, 0xbfb8aa3b, v2
	v_exp_f32_e32 v2, v2
	v_pk_add_f32 v[144:145], v[144:145], 1.0 op_sel_hi:[1,0]
	v_exp_f32_e32 v1, v1
	v_add_f32_e32 v2, 1.0, v2
	v_rcp_f32_e32 v141, v2
	v_and_b32_e32 v2, 0xffff0000, v142
	v_mul_f32_e32 v2, 0xbfb8aa3b, v2
	v_exp_f32_e32 v2, v2
	v_pk_mul_f32 v[140:141], v[144:145], v[140:141]
	v_pk_add_f32 v[0:1], v[0:1], 1.0 op_sel_hi:[1,0]
	v_pk_mul_f32 v[18:19], v[18:19], v[140:141]
	v_add_f32_e32 v2, 1.0, v2
	v_rcp_f32_e32 v141, v2
	v_lshlrev_b32_e32 v2, 16, v147
	v_mul_f32_e32 v2, 0xbfb8aa3b, v2
	v_exp_f32_e32 v144, v2
	v_lshlrev_b32_e32 v2, 16, v143
	v_mul_f32_e32 v2, 0xbfb8aa3b, v2
	v_pk_mul_f32 v[0:1], v[0:1], v[148:149]
	v_exp_f32_e32 v2, v2
	v_pk_mul_f32 v[16:17], v[16:17], v[0:1]
	v_lshlrev_b32_e32 v1, 16, v142
	v_mul_f32_e32 v1, 0xbfb8aa3b, v1
	v_exp_f32_e32 v1, v1
	v_add_f32_e32 v2, 1.0, v2
	v_rcp_f32_e32 v142, v2
	v_and_b32_e32 v2, 0xffff0000, v147
	v_mul_f32_e32 v2, 0xbfb8aa3b, v2
	v_add_f32_e32 v1, 1.0, v1
	v_exp_f32_e32 v145, v2
	v_and_b32_e32 v2, 0xffff0000, v143
	v_lshlrev_b32_e32 v0, 16, v146
	v_rcp_f32_e32 v140, v1
	v_and_b32_e32 v1, 0xffff0000, v146
	v_mul_f32_e32 v2, 0xbfb8aa3b, v2
	v_mul_f32_e32 v0, 0xbfb8aa3b, v0
	v_mul_f32_e32 v1, 0xbfb8aa3b, v1
	v_exp_f32_e32 v2, v2
	v_exp_f32_e32 v0, v0
	v_exp_f32_e32 v1, v1
	v_pk_add_f32 v[144:145], v[144:145], 1.0 op_sel_hi:[1,0]
	v_add_f32_e32 v2, 1.0, v2
	v_rcp_f32_e32 v143, v2
	v_pk_add_f32 v[0:1], v[0:1], 1.0 op_sel_hi:[1,0]
	v_and_b32_e32 v2, 0xffff0000, v132
	v_pk_mul_f32 v[0:1], v[0:1], v[140:141]
	v_mul_f32_e32 v2, 0xbfb8aa3b, v2
	v_pk_mul_f32 v[12:13], v[12:13], v[0:1]
	v_lshlrev_b32_e32 v1, 16, v132
	v_exp_f32_e32 v2, v2
	v_mul_f32_e32 v1, 0xbfb8aa3b, v1
	v_exp_f32_e32 v1, v1
	v_pk_mul_f32 v[140:141], v[144:145], v[142:143]
	v_add_f32_e32 v2, 1.0, v2
	v_pk_mul_f32 v[14:15], v[14:15], v[140:141]
	v_rcp_f32_e32 v141, v2
	v_lshlrev_b32_e32 v2, 16, v137
	v_add_f32_e32 v1, 1.0, v1
	v_mul_f32_e32 v2, 0xbfb8aa3b, v2
	v_lshlrev_b32_e32 v0, 16, v136
	v_rcp_f32_e32 v140, v1
	v_and_b32_e32 v1, 0xffff0000, v136
	v_exp_f32_e32 v136, v2
	v_lshlrev_b32_e32 v2, 16, v133
	v_mul_f32_e32 v2, 0xbfb8aa3b, v2
	v_exp_f32_e32 v2, v2
	v_mul_f32_e32 v0, 0xbfb8aa3b, v0
	v_mul_f32_e32 v1, 0xbfb8aa3b, v1
	v_exp_f32_e32 v0, v0
	v_add_f32_e32 v2, 1.0, v2
	v_rcp_f32_e32 v132, v2
	v_and_b32_e32 v2, 0xffff0000, v137
	v_mul_f32_e32 v2, 0xbfb8aa3b, v2
	v_exp_f32_e32 v137, v2
	v_and_b32_e32 v2, 0xffff0000, v133
	v_mul_f32_e32 v2, 0xbfb8aa3b, v2
	v_exp_f32_e32 v2, v2
	v_pk_add_f32 v[136:137], v[136:137], 1.0 op_sel_hi:[1,0]
	v_exp_f32_e32 v1, v1
	v_add_f32_e32 v2, 1.0, v2
	v_rcp_f32_e32 v133, v2
	v_and_b32_e32 v2, 0xffff0000, v134
	v_mul_f32_e32 v2, 0xbfb8aa3b, v2
	v_exp_f32_e32 v2, v2
	v_pk_mul_f32 v[132:133], v[136:137], v[132:133]
	v_pk_add_f32 v[0:1], v[0:1], 1.0 op_sel_hi:[1,0]
	v_pk_mul_f32 v[10:11], v[10:11], v[132:133]
	v_add_f32_e32 v2, 1.0, v2
	v_rcp_f32_e32 v133, v2
	v_lshlrev_b32_e32 v2, 16, v139
	v_mul_f32_e32 v2, 0xbfb8aa3b, v2
	v_exp_f32_e32 v136, v2
	v_lshlrev_b32_e32 v2, 16, v135
	v_mul_f32_e32 v2, 0xbfb8aa3b, v2
	v_exp_f32_e32 v2, v2
	v_pk_mul_f32 v[0:1], v[0:1], v[140:141]
	v_add_f32_e32 v2, 1.0, v2
	v_pk_mul_f32 v[8:9], v[8:9], v[0:1]
	v_lshlrev_b32_e32 v1, 16, v134
	v_mul_f32_e32 v1, 0xbfb8aa3b, v1
	v_rcp_f32_e32 v134, v2
	v_and_b32_e32 v2, 0xffff0000, v139
	v_exp_f32_e32 v1, v1
	v_mul_f32_e32 v2, 0xbfb8aa3b, v2
	v_exp_f32_e32 v137, v2
	v_and_b32_e32 v2, 0xffff0000, v135
	v_mul_f32_e32 v2, 0xbfb8aa3b, v2
	v_exp_f32_e32 v2, v2
	v_add_f32_e32 v1, 1.0, v1
	v_lshlrev_b32_e32 v0, 16, v138
	v_rcp_f32_e32 v132, v1
	v_and_b32_e32 v1, 0xffff0000, v138
	v_mul_f32_e32 v0, 0xbfb8aa3b, v0
	v_mul_f32_e32 v1, 0xbfb8aa3b, v1
	v_exp_f32_e32 v0, v0
	v_exp_f32_e32 v1, v1
	v_add_f32_e32 v2, 1.0, v2
	v_rcp_f32_e32 v135, v2
	v_pk_add_f32 v[136:137], v[136:137], 1.0 op_sel_hi:[1,0]
	v_pk_add_f32 v[0:1], v[0:1], 1.0 op_sel_hi:[1,0]
	s_nop 0
	v_pk_mul_f32 v[0:1], v[0:1], v[132:133]
	v_pk_mul_f32 v[132:133], v[136:137], v[134:135]
	v_pk_mul_f32 v[4:5], v[4:5], v[0:1]
	v_pk_mul_f32 v[6:7], v[6:7], v[132:133]
	s_branch .LBB0_520
; #define LAS __attribute__((address_space(3)))
; template <class Epi, int LDA, int LDB, int KK>
; __device__ __forceinline__ void gemm_phase(int wv, LAS unsigned char* lds, const Gemm g, const StaticOrder& S, const Epi& E) {
;     ...
;           if constexpr (Epi::HAS_MID) { if (seg < Epi::NSEG - 1) E.mid(acc, cur, seg, wr, wc, fr, fq); }
;         }
;         E(acc, cur, wr, wc, fr, fq, (const LAS float*)(lds + 131072 + (ui % 3) * 1024));
;         if (!has_next) break;
; #pragma unroll
;         for (int a = 0; a < 2; ++a)
; #pragma unroll
;             for (int b = 0; b < 2; ++b)
; #pragma unroll
;                 for (int m = 0; m < 4; ++m)
; #pragma unroll
;                     for (int n = 0; n < 2; ++n) acc[a][b][m][n] = (f32x4){0.f, 0.f, 0.f, 0.f};
;         cur = nxt; cA = nA; cB = nB; ++ui;
;     }
.Lmt_prod:
	s_and_b32 s98, s81, 15
	s_mul_i32 s98, s98, 3
	s_add_u32 s98, s98, s100
	s_sub_u32 s98, s98, 2
	s_lshl_b32 s98, s98, 18
	s_add_u32 s98, s98, 0x7c00000
	s_add_u32 s98, s10, s98
	s_addc_u32 s99, s11, 0
	v_mbcnt_lo_u32_b32 v132, -1, 0
	v_mbcnt_hi_u32_b32 v132, -1, v132
	v_lshl_or_b32 v132, s95, 6, v132
	v_lshlrev_b32_e32 v132, 4, v132
	global_store_dwordx4 v132, v[4:7], s[98:99] sc0 sc1
	v_add_u32_e32 v132, 0x2000, v132
	global_store_dwordx4 v132, v[8:11], s[98:99] sc0 sc1
	v_add_u32_e32 v132, 0x2000, v132
	global_store_dwordx4 v132, v[12:15], s[98:99] sc0 sc1
	v_add_u32_e32 v132, 0x2000, v132
	global_store_dwordx4 v132, v[16:19], s[98:99] sc0 sc1
	v_add_u32_e32 v132, 0x2000, v132
	global_store_dwordx4 v132, v[20:23], s[98:99] sc0 sc1
	v_add_u32_e32 v132, 0x2000, v132
	global_store_dwordx4 v132, v[24:27], s[98:99] sc0 sc1
	v_add_u32_e32 v132, 0x2000, v132
	global_store_dwordx4 v132, v[28:31], s[98:99] sc0 sc1
	v_add_u32_e32 v132, 0x2000, v132
	global_store_dwordx4 v132, v[32:35], s[98:99] sc0 sc1
	v_add_u32_e32 v132, 0x2000, v132
	global_store_dwordx4 v132, v[36:39], s[98:99] sc0 sc1
	v_add_u32_e32 v132, 0x2000, v132
	global_store_dwordx4 v132, v[40:43], s[98:99] sc0 sc1
	v_add_u32_e32 v132, 0x2000, v132
	global_store_dwordx4 v132, v[44:47], s[98:99] sc0 sc1
	v_add_u32_e32 v132, 0x2000, v132
	global_store_dwordx4 v132, v[48:51], s[98:99] sc0 sc1
	v_add_u32_e32 v132, 0x2000, v132
	global_store_dwordx4 v132, v[52:55], s[98:99] sc0 sc1
	v_add_u32_e32 v132, 0x2000, v132
	global_store_dwordx4 v132, v[56:59], s[98:99] sc0 sc1
	v_add_u32_e32 v132, 0x2000, v132
	global_store_dwordx4 v132, v[60:63], s[98:99] sc0 sc1
	v_add_u32_e32 v132, 0x2000, v132
	global_store_dwordx4 v132, v[64:67], s[98:99] sc0 sc1
	v_add_u32_e32 v132, 0x2000, v132
	global_store_dwordx4 v132, v[68:71], s[98:99] sc0 sc1
	v_add_u32_e32 v132, 0x2000, v132
	global_store_dwordx4 v132, v[72:75], s[98:99] sc0 sc1
	v_add_u32_e32 v132, 0x2000, v132
	global_store_dwordx4 v132, v[76:79], s[98:99] sc0 sc1
	v_add_u32_e32 v132, 0x2000, v132
	global_store_dwordx4 v132, v[80:83], s[98:99] sc0 sc1
	v_add_u32_e32 v132, 0x2000, v132
	global_store_dwordx4 v132, v[84:87], s[98:99] sc0 sc1
	v_add_u32_e32 v132, 0x2000, v132
	global_store_dwordx4 v132, v[88:91], s[98:99] sc0 sc1
	v_add_u32_e32 v132, 0x2000, v132
	global_store_dwordx4 v132, v[92:95], s[98:99] sc0 sc1
	v_add_u32_e32 v132, 0x2000, v132
	global_store_dwordx4 v132, v[96:99], s[98:99] sc0 sc1
	v_add_u32_e32 v132, 0x2000, v132
	global_store_dwordx4 v132, v[100:103], s[98:99] sc0 sc1
	v_add_u32_e32 v132, 0x2000, v132
	global_store_dwordx4 v132, v[104:107], s[98:99] sc0 sc1
	v_add_u32_e32 v132, 0x2000, v132
	global_store_dwordx4 v132, v[108:111], s[98:99] sc0 sc1
	v_add_u32_e32 v132, 0x2000, v132
	global_store_dwordx4 v132, v[112:115], s[98:99] sc0 sc1
	v_add_u32_e32 v132, 0x2000, v132
	global_store_dwordx4 v132, v[116:119], s[98:99] sc0 sc1
	v_add_u32_e32 v132, 0x2000, v132
	global_store_dwordx4 v132, v[120:123], s[98:99] sc0 sc1
	v_add_u32_e32 v132, 0x2000, v132
	global_store_dwordx4 v132, v[124:127], s[98:99] sc0 sc1
	v_add_u32_e32 v132, 0x2000, v132
	global_store_dwordx4 v132, v[128:131], s[98:99] sc0 sc1
	s_waitcnt vmcnt(0)
	s_barrier
	s_cmp_lg_u32 s95, 0
	s_cbranch_scc1 .Lmt_p_done
	s_and_b32 s98, s81, 15
	s_lshl_b32 s98, s98, 2
	s_add_u32 s98, s98, 0x201daa80
	s_add_u32 s98, s10, s98
	s_addc_u32 s99, s11, 0
	s_mov_b64 exec, 1
	v_mov_b32_e32 v132, 0
	v_mov_b32_e32 v133, 1
	global_atomic_add v132, v133, s[98:99]
	s_mov_b64 exec, -1
.Lmt_p_done:
	s_mov_b32 s23, s12
	s_mov_b32 s22, s14
	s_mov_b64 s[24:25], s[18:19]
	s_mov_b64 s[20:21], s[16:17]
	s_and_b64 vcc, exec, s[4:5]
	s_cbranch_vccnz .LBB0_526
	s_branch .LBB0_517
